# speedup vs baseline: 1.0374x; 1.0374x over previous
.LBB0_604:
	s_and_b32 s62, s94, 1
	s_bfe_i32 s63, s94, 0x10000
	s_cmp_eq_u32 s62, 0
	s_cselect_b64 s[96:97], -1, 0
	s_and_b32 s62, s63, 0xb20
	s_cmp_eq_u32 s94, 0
	s_cbranch_scc1 .Lscan_top_strict
	s_and_b64 s[70:71], exec, s[10:11]
	s_cbranch_scc0 .Lscan_top_strict
	s_waitcnt vmcnt(28)
	ds_write_b128 v163, v[50:53]
	s_waitcnt vmcnt(26)
	ds_write_b128 v163, v[54:57] offset:33792
	s_waitcnt vmcnt(23)
	ds_write_b128 v163, v[62:65] offset:8448
	s_waitcnt vmcnt(22)
	ds_write_b128 v163, v[66:69] offset:42240
	s_waitcnt vmcnt(20)
	ds_write_b128 v163, v[74:77] offset:16896
	s_waitcnt vmcnt(19)
	ds_write_b128 v163, v[78:81] offset:50688
	ds_write_b128 v163, v[86:89] offset:25344
	s_waitcnt vmcnt(18)
	ds_write_b128 v163, v[90:93] offset:59136
	s_waitcnt vmcnt(16)
	ds_write_b128 v148, v[98:101]
	s_branch .Lscan_top_done
.Lscan_top_strict:
	s_waitcnt vmcnt(12)
	ds_write_b128 v163, v[50:53]
	s_waitcnt vmcnt(10)
	ds_write_b128 v163, v[54:57] offset:33792
	s_waitcnt vmcnt(7)
	ds_write_b128 v163, v[62:65] offset:8448
	s_waitcnt vmcnt(6)
	ds_write_b128 v163, v[66:69] offset:42240
	s_waitcnt vmcnt(4)
	ds_write_b128 v163, v[74:77] offset:16896
	s_waitcnt vmcnt(3)
	ds_write_b128 v163, v[78:81] offset:50688
	ds_write_b128 v163, v[86:89] offset:25344
	s_waitcnt vmcnt(2)
	ds_write_b128 v163, v[90:93] offset:59136
	s_waitcnt vmcnt(0)
	ds_write_b128 v148, v[98:101]
.Lscan_top_done:
	s_or_b32 s69, s62, 0x26400
	s_waitcnt lgkmcnt(0)
	s_barrier
	v_lshl_add_u32 v46, v143, 2, s69
	ds_read_b128 v[34:37], v46 offset:1024
	ds_read_b128 v[38:41], v46 offset:1040
	v_lshlrev_b32_e32 v43, 16, v59
	v_lshlrev_b32_e32 v42, 16, v58
	s_add_i32 s82, s94, 1
	s_waitcnt lgkmcnt(1)
	v_mov_b32_e32 v44, v34
	v_mov_b32_e32 v45, v36
	v_pk_mul_f32 v[42:43], v[44:45], v[42:43]
	v_and_b32_e32 v45, 0xffff0000, v59
	v_and_b32_e32 v44, 0xffff0000, v58
	v_mov_b32_e32 v36, v35
	v_pk_mul_f32 v[34:35], v[36:37], v[44:45]
	v_cvt_pk_bf16_f32 v36, v42, v43
	v_cvt_pk_bf16_f32 v34, v34, v35
	v_and_b32_e32 v35, 0xffff0000, v34
	v_lshlrev_b32_e32 v34, 16, v34
	v_or_b32_sdwa v35, v35, v36 dst_sel:DWORD dst_unused:UNUSED_PAD src0_sel:DWORD src1_sel:WORD_1
	v_or_b32_sdwa v34, v34, v36 dst_sel:DWORD dst_unused:UNUSED_PAD src0_sel:DWORD src1_sel:WORD_0
	v_lshlrev_b32_e32 v37, 16, v61
	v_lshlrev_b32_e32 v36, 16, v60
	s_waitcnt lgkmcnt(0)
	v_mov_b32_e32 v42, v38
	v_mov_b32_e32 v43, v40
	v_pk_mul_f32 v[36:37], v[42:43], v[36:37]
	v_and_b32_e32 v43, 0xffff0000, v61
	v_and_b32_e32 v42, 0xffff0000, v60
	v_mov_b32_e32 v40, v39
	v_pk_mul_f32 v[38:39], v[40:41], v[42:43]
	v_cvt_pk_bf16_f32 v36, v36, v37
	v_cvt_pk_bf16_f32 v37, v38, v39
	v_and_b32_e32 v38, 0xffff0000, v37
	v_lshlrev_b32_e32 v39, 16, v37
	v_or_b32_sdwa v37, v38, v36 dst_sel:DWORD dst_unused:UNUSED_PAD src0_sel:DWORD src1_sel:WORD_1
	v_or_b32_sdwa v36, v39, v36 dst_sel:DWORD dst_unused:UNUSED_PAD src0_sel:DWORD src1_sel:WORD_0
	v_add_u32_e32 v38, v149, v147
	ds_write_b128 v38, v[34:37]
	ds_read_b128 v[34:37], v46 offset:1024
	ds_read_b128 v[38:41], v46 offset:1040
	v_lshlrev_b32_e32 v43, 16, v71
	v_lshlrev_b32_e32 v42, 16, v70
	s_cmp_ge_u32 s82, s66
	s_waitcnt lgkmcnt(1)
	v_mov_b32_e32 v44, v34
	v_mov_b32_e32 v45, v36
	v_pk_mul_f32 v[42:43], v[44:45], v[42:43]
	v_and_b32_e32 v45, 0xffff0000, v71
	v_and_b32_e32 v44, 0xffff0000, v70
	v_mov_b32_e32 v36, v35
	v_pk_mul_f32 v[34:35], v[36:37], v[44:45]
	v_cvt_pk_bf16_f32 v36, v42, v43
	v_cvt_pk_bf16_f32 v34, v34, v35
	v_and_b32_e32 v35, 0xffff0000, v34
	v_lshlrev_b32_e32 v34, 16, v34
	v_or_b32_sdwa v35, v35, v36 dst_sel:DWORD dst_unused:UNUSED_PAD src0_sel:DWORD src1_sel:WORD_1
	v_or_b32_sdwa v34, v34, v36 dst_sel:DWORD dst_unused:UNUSED_PAD src0_sel:DWORD src1_sel:WORD_0
	v_lshlrev_b32_e32 v37, 16, v73
	v_lshlrev_b32_e32 v36, 16, v72
	s_waitcnt lgkmcnt(0)
	v_mov_b32_e32 v42, v38
	v_mov_b32_e32 v43, v40
	v_pk_mul_f32 v[36:37], v[42:43], v[36:37]
	v_and_b32_e32 v43, 0xffff0000, v73
	v_and_b32_e32 v42, 0xffff0000, v72
	v_mov_b32_e32 v40, v39
	v_pk_mul_f32 v[38:39], v[40:41], v[42:43]
	v_cvt_pk_bf16_f32 v36, v36, v37
	v_cvt_pk_bf16_f32 v37, v38, v39
	v_and_b32_e32 v38, 0xffff0000, v37
	v_lshlrev_b32_e32 v39, 16, v37
	v_or_b32_sdwa v37, v38, v36 dst_sel:DWORD dst_unused:UNUSED_PAD src0_sel:DWORD src1_sel:WORD_1
	v_or_b32_sdwa v36, v39, v36 dst_sel:DWORD dst_unused:UNUSED_PAD src0_sel:DWORD src1_sel:WORD_0
	ds_write_b128 v172, v[34:37]
	ds_read_b128 v[34:37], v46 offset:1024
	ds_read_b128 v[38:41], v46 offset:1040
	v_lshlrev_b32_e32 v43, 16, v83
	v_lshlrev_b32_e32 v42, 16, v82
	s_cselect_b64 s[62:63], -1, 0
	s_waitcnt lgkmcnt(1)
	v_mov_b32_e32 v44, v34
	v_mov_b32_e32 v45, v36
	v_pk_mul_f32 v[42:43], v[44:45], v[42:43]
	v_and_b32_e32 v45, 0xffff0000, v83
	v_and_b32_e32 v44, 0xffff0000, v82
	v_mov_b32_e32 v36, v35
	v_pk_mul_f32 v[34:35], v[36:37], v[44:45]
	v_cvt_pk_bf16_f32 v36, v42, v43
	v_cvt_pk_bf16_f32 v34, v34, v35
	v_and_b32_e32 v35, 0xffff0000, v34
	v_lshlrev_b32_e32 v34, 16, v34
	v_or_b32_sdwa v35, v35, v36 dst_sel:DWORD dst_unused:UNUSED_PAD src0_sel:DWORD src1_sel:WORD_1
	v_or_b32_sdwa v34, v34, v36 dst_sel:DWORD dst_unused:UNUSED_PAD src0_sel:DWORD src1_sel:WORD_0
	v_lshlrev_b32_e32 v37, 16, v85
	v_lshlrev_b32_e32 v36, 16, v84
	s_waitcnt lgkmcnt(0)
	v_mov_b32_e32 v42, v38
	v_mov_b32_e32 v43, v40
	v_pk_mul_f32 v[36:37], v[42:43], v[36:37]
	v_and_b32_e32 v43, 0xffff0000, v85
	v_and_b32_e32 v42, 0xffff0000, v84
	v_mov_b32_e32 v40, v39
	v_pk_mul_f32 v[38:39], v[40:41], v[42:43]
	v_cvt_pk_bf16_f32 v36, v36, v37
	v_cvt_pk_bf16_f32 v37, v38, v39
	v_and_b32_e32 v38, 0xffff0000, v37
	v_lshlrev_b32_e32 v39, 16, v37
	v_or_b32_sdwa v37, v38, v36 dst_sel:DWORD dst_unused:UNUSED_PAD src0_sel:DWORD src1_sel:WORD_1
	v_or_b32_sdwa v36, v39, v36 dst_sel:DWORD dst_unused:UNUSED_PAD src0_sel:DWORD src1_sel:WORD_0
	ds_write_b128 v172, v[34:37] offset:9216
	ds_read_b128 v[34:37], v46 offset:1024
	ds_read_b128 v[38:41], v46 offset:1040
	v_lshlrev_b32_e32 v43, 16, v95
	v_lshlrev_b32_e32 v42, 16, v94
	s_and_b64 vcc, exec, s[62:63]
	s_waitcnt lgkmcnt(1)
	v_mov_b32_e32 v44, v34
	v_mov_b32_e32 v45, v36
	v_pk_mul_f32 v[42:43], v[44:45], v[42:43]
	v_and_b32_e32 v45, 0xffff0000, v95
	v_and_b32_e32 v44, 0xffff0000, v94
	v_mov_b32_e32 v36, v35
	v_pk_mul_f32 v[34:35], v[36:37], v[44:45]
	v_cvt_pk_bf16_f32 v36, v42, v43
	v_cvt_pk_bf16_f32 v34, v34, v35
	v_and_b32_e32 v35, 0xffff0000, v34
	v_lshlrev_b32_e32 v34, 16, v34
	v_or_b32_sdwa v35, v35, v36 dst_sel:DWORD dst_unused:UNUSED_PAD src0_sel:DWORD src1_sel:WORD_1
	v_or_b32_sdwa v34, v34, v36 dst_sel:DWORD dst_unused:UNUSED_PAD src0_sel:DWORD src1_sel:WORD_0
	v_lshlrev_b32_e32 v37, 16, v97
	v_lshlrev_b32_e32 v36, 16, v96
	s_waitcnt lgkmcnt(0)
	v_mov_b32_e32 v42, v38
	v_mov_b32_e32 v43, v40
	v_pk_mul_f32 v[36:37], v[42:43], v[36:37]
	v_and_b32_e32 v43, 0xffff0000, v97
	v_and_b32_e32 v42, 0xffff0000, v96
	v_mov_b32_e32 v40, v39
	v_pk_mul_f32 v[38:39], v[40:41], v[42:43]
	v_cvt_pk_bf16_f32 v36, v36, v37
	v_cvt_pk_bf16_f32 v37, v38, v39
	v_and_b32_e32 v38, 0xffff0000, v37
	v_lshlrev_b32_e32 v39, 16, v37
	v_or_b32_sdwa v37, v38, v36 dst_sel:DWORD dst_unused:UNUSED_PAD src0_sel:DWORD src1_sel:WORD_1
	v_or_b32_sdwa v36, v39, v36 dst_sel:DWORD dst_unused:UNUSED_PAD src0_sel:DWORD src1_sel:WORD_0
	ds_write_b128 v172, v[34:37] offset:18432
	s_cbranch_vccnz .LBB0_608
	s_lshl_b64 s[70:71], s[82:83], 17
	s_add_u32 s76, s88, s70
	s_addc_u32 s77, s89, s71
	s_add_u32 s70, s90, s70
	s_addc_u32 s71, s91, s71
	s_lshl_b32 s78, s82, 7
	s_add_u32 vcc_lo, s92, s78
	v_lshl_add_u64 v[34:35], s[76:77], 0, v[104:105]
	s_addc_u32 vcc_hi, s93, 0
	global_load_dwordx4 v[50:53], v[34:35], off
	v_lshl_add_u64 v[34:35], s[70:71], 0, v[104:105]
	global_load_dwordx4 v[54:57], v[34:35], off
	v_lshl_add_u64 v[34:35], v[0:1], 1, vcc
	global_load_dwordx4 v[58:61], v[34:35], off
	v_lshl_add_u64 v[34:35], s[76:77], 0, v[106:107]
	global_load_dwordx4 v[62:65], v[34:35], off
	v_lshl_add_u64 v[34:35], s[70:71], 0, v[106:107]
	global_load_dwordx4 v[66:69], v[34:35], off
	v_lshl_add_u64 v[34:35], v[108:109], 1, vcc
	global_load_dwordx4 v[70:73], v[34:35], off
	v_lshl_add_u64 v[34:35], s[76:77], 0, v[110:111]
	global_load_dwordx4 v[74:77], v[34:35], off
	v_lshl_add_u64 v[34:35], s[70:71], 0, v[110:111]
	global_load_dwordx4 v[78:81], v[34:35], off
	v_lshl_add_u64 v[34:35], v[112:113], 1, vcc
	global_load_dwordx4 v[82:85], v[34:35], off
	v_lshl_add_u64 v[34:35], s[76:77], 0, v[114:115]
	global_load_dwordx4 v[86:89], v[34:35], off
	v_lshl_add_u64 v[34:35], s[70:71], 0, v[114:115]
	s_mov_b32 s79, s83
	global_load_dwordx4 v[90:93], v[34:35], off
	v_lshl_add_u64 v[34:35], v[116:117], 1, vcc
	global_load_dwordx4 v[94:97], v[34:35], off
	v_lshl_add_u64 v[34:35], v[118:119], 0, s[78:79]
	global_load_dwordx4 v[98:101], v[34:35], off nt
	s_and_saveexec_b64 s[76:77], s[8:9]
	s_cbranch_execz .LBB0_607
	s_lshl_b32 s70, s82, 6
	s_add_i32 s70, s70, s86
	s_ashr_i32 s71, s70, 31
	s_lshl_b64 s[70:71], s[70:71], 5
	v_lshl_add_u64 v[34:35], v[120:121], 0, s[70:71]
	global_load_dword v144, v[34:35], off
	global_load_dword v145, v[34:35], off offset:16

.LBB0_608:
	s_and_saveexec_b64 s[70:71], s[10:11]
	s_xor_b64 s[76:77], exec, s[70:71]
	s_cbranch_execz .LBB0_611
	v_add_u32_e32 v213, 0x1e000, v169
	ds_read_b128 v[214:217], v150
	ds_read_b128 v[218:221], v213
	ds_read_b128 v[222:225], v150 offset:32
	ds_read_b128 v[226:229], v213 offset:32
	ds_read_b128 v[230:233], v150 offset:64
	ds_read_b128 v[234:237], v213 offset:64
	ds_read_b128 v[238:241], v150 offset:96
	ds_read_b128 v[242:245], v213 offset:96
	s_waitcnt lgkmcnt(6)
	v_mfma_f32_32x32x16_bf16 v[34:49], v[214:217], v[218:221], 0
	ds_read_b128 v[214:217], v150 offset:128
	ds_read_b128 v[218:221], v213 offset:128
	s_waitcnt lgkmcnt(6)
	v_mfma_f32_32x32x16_bf16 v[34:49], v[222:225], v[226:229], v[34:49]
	ds_read_b128 v[222:225], v150 offset:160
	ds_read_b128 v[226:229], v213 offset:160
	s_waitcnt lgkmcnt(6)
	v_mfma_f32_32x32x16_bf16 v[34:49], v[230:233], v[234:237], v[34:49]
	ds_read_b128 v[230:233], v150 offset:192
	ds_read_b128 v[234:237], v213 offset:192
	s_waitcnt lgkmcnt(6)
	v_mfma_f32_32x32x16_bf16 v[34:49], v[238:241], v[242:245], v[34:49]
	ds_read_b128 v[238:241], v150 offset:224
	ds_read_b128 v[242:245], v213 offset:224
	s_waitcnt lgkmcnt(6)
	v_mfma_f32_32x32x16_bf16 v[34:49], v[214:217], v[218:221], v[34:49]
	ds_read_b128 v[214:217], v150 offset:256
	ds_read_b128 v[218:221], v213 offset:256
	s_waitcnt lgkmcnt(6)
	v_mfma_f32_32x32x16_bf16 v[34:49], v[222:225], v[226:229], v[34:49]
	ds_read_b128 v[222:225], v150 offset:288
	ds_read_b128 v[226:229], v213 offset:288
	s_waitcnt lgkmcnt(6)
	v_mfma_f32_32x32x16_bf16 v[34:49], v[230:233], v[234:237], v[34:49]
	ds_read_b128 v[230:233], v150 offset:320
	ds_read_b128 v[234:237], v213 offset:320
	s_waitcnt lgkmcnt(6)
	v_mfma_f32_32x32x16_bf16 v[34:49], v[238:241], v[242:245], v[34:49]
	ds_read_b128 v[238:241], v150 offset:352
	ds_read_b128 v[242:245], v213 offset:352
	s_waitcnt lgkmcnt(6)
	v_mfma_f32_32x32x16_bf16 v[34:49], v[214:217], v[218:221], v[34:49]
	ds_read_b128 v[214:217], v150 offset:384
	ds_read_b128 v[218:221], v213 offset:384
	s_waitcnt lgkmcnt(6)
	v_mfma_f32_32x32x16_bf16 v[34:49], v[222:225], v[226:229], v[34:49]
	ds_read_b128 v[222:225], v150 offset:416
	ds_read_b128 v[226:229], v213 offset:416
	s_waitcnt lgkmcnt(6)
	v_mfma_f32_32x32x16_bf16 v[34:49], v[230:233], v[234:237], v[34:49]
	ds_read_b128 v[230:233], v150 offset:448
	ds_read_b128 v[234:237], v213 offset:448
	s_waitcnt lgkmcnt(6)
	v_mfma_f32_32x32x16_bf16 v[34:49], v[238:241], v[242:245], v[34:49]
	ds_read_b128 v[238:241], v150 offset:480
	ds_read_b128 v[242:245], v213 offset:480
	s_waitcnt lgkmcnt(6)
	v_mfma_f32_32x32x16_bf16 v[34:49], v[214:217], v[218:221], v[34:49]
	s_waitcnt lgkmcnt(4)
	v_mfma_f32_32x32x16_bf16 v[34:49], v[222:225], v[226:229], v[34:49]
	s_waitcnt lgkmcnt(2)
	v_mfma_f32_32x32x16_bf16 v[34:49], v[230:233], v[234:237], v[34:49]
	s_waitcnt lgkmcnt(0)
	v_mfma_f32_32x32x16_bf16 v[34:49], v[238:241], v[242:245], v[34:49]
.LBB0_611:
	s_andn2_saveexec_b64 s[76:77], s[76:77]
	s_cbranch_execz .LBB0_651
	ds_read_b128 v[214:217], v150
	ds_read_b128 v[218:221], v170
	ds_read_b128 v[222:225], v150 offset:32
	ds_read_b128 v[226:229], v170 offset:32
	ds_read_b128 v[230:233], v150 offset:64
	ds_read_b128 v[234:237], v170 offset:64
	ds_read_b128 v[238:241], v150 offset:96
	ds_read_b128 v[242:245], v170 offset:96
	s_waitcnt lgkmcnt(6)
	v_mfma_f32_32x32x16_bf16 v[34:49], v[214:217], v[218:221], 0
	ds_read_b128 v[214:217], v150 offset:128
	ds_read_b128 v[218:221], v170 offset:128
	s_waitcnt lgkmcnt(6)
	v_mfma_f32_32x32x16_bf16 v[34:49], v[222:225], v[226:229], v[34:49]
	ds_read_b128 v[222:225], v150 offset:160
	ds_read_b128 v[226:229], v170 offset:160
	s_waitcnt lgkmcnt(6)
	v_mfma_f32_32x32x16_bf16 v[34:49], v[230:233], v[234:237], v[34:49]
	ds_read_b128 v[230:233], v150 offset:192
	ds_read_b128 v[234:237], v170 offset:192
	s_waitcnt lgkmcnt(6)
	v_mfma_f32_32x32x16_bf16 v[34:49], v[238:241], v[242:245], v[34:49]
	ds_read_b128 v[238:241], v150 offset:224
	ds_read_b128 v[242:245], v170 offset:224
	s_waitcnt lgkmcnt(6)
	v_mfma_f32_32x32x16_bf16 v[34:49], v[214:217], v[218:221], v[34:49]
	ds_read_b128 v[214:217], v150 offset:256
	ds_read_b128 v[218:221], v170 offset:256
	s_waitcnt lgkmcnt(6)
	v_mfma_f32_32x32x16_bf16 v[34:49], v[222:225], v[226:229], v[34:49]
	ds_read_b128 v[222:225], v150 offset:288
	ds_read_b128 v[226:229], v170 offset:288
	s_waitcnt lgkmcnt(6)
	v_mfma_f32_32x32x16_bf16 v[34:49], v[230:233], v[234:237], v[34:49]
	ds_read_b128 v[230:233], v150 offset:320
	ds_read_b128 v[234:237], v170 offset:320
	s_waitcnt lgkmcnt(6)
	v_mfma_f32_32x32x16_bf16 v[34:49], v[238:241], v[242:245], v[34:49]
	ds_read_b128 v[238:241], v150 offset:352
	ds_read_b128 v[242:245], v170 offset:352
	s_waitcnt lgkmcnt(6)
	v_mfma_f32_32x32x16_bf16 v[34:49], v[214:217], v[218:221], v[34:49]
	ds_read_b128 v[214:217], v150 offset:384
	ds_read_b128 v[218:221], v170 offset:384
	s_waitcnt lgkmcnt(6)
	v_mfma_f32_32x32x16_bf16 v[34:49], v[222:225], v[226:229], v[34:49]
	ds_read_b128 v[222:225], v150 offset:416
	ds_read_b128 v[226:229], v170 offset:416
	s_waitcnt lgkmcnt(6)
	v_mfma_f32_32x32x16_bf16 v[34:49], v[230:233], v[234:237], v[34:49]
	ds_read_b128 v[230:233], v150 offset:448
	ds_read_b128 v[234:237], v170 offset:448
	s_waitcnt lgkmcnt(6)
	v_mfma_f32_32x32x16_bf16 v[34:49], v[238:241], v[242:245], v[34:49]
	ds_read_b128 v[238:241], v150 offset:480
	ds_read_b128 v[242:245], v170 offset:480
	s_waitcnt lgkmcnt(6)
	v_mfma_f32_32x32x16_bf16 v[34:49], v[214:217], v[218:221], v[34:49]
	s_waitcnt lgkmcnt(4)
	v_mfma_f32_32x32x16_bf16 v[34:49], v[222:225], v[226:229], v[34:49]
	s_waitcnt lgkmcnt(2)
	v_mfma_f32_32x32x16_bf16 v[34:49], v[230:233], v[234:237], v[34:49]
	s_waitcnt lgkmcnt(0)
	v_mfma_f32_32x32x16_bf16 v[34:49], v[238:241], v[242:245], v[34:49]
	v_lshl_add_u32 v122, v151, 2, s69
	v_lshl_add_u32 v193, v152, 2, s69
	ds_read_b32 v122, v122
	ds_read_b128 v[214:217], v193 offset:256
	ds_read_b128 v[218:221], v193 offset:288
	ds_read_b128 v[222:225], v193 offset:320
	ds_read_b128 v[226:229], v193 offset:352
	s_waitcnt lgkmcnt(0)
	v_sub_f32_e32 v214, v122, v214
	v_sub_f32_e32 v215, v122, v215
	v_sub_f32_e32 v216, v122, v216
	v_sub_f32_e32 v217, v122, v217
	v_sub_f32_e32 v218, v122, v218
	v_sub_f32_e32 v219, v122, v219
	v_sub_f32_e32 v220, v122, v220
	v_sub_f32_e32 v221, v122, v221
	v_sub_f32_e32 v222, v122, v222
	v_sub_f32_e32 v223, v122, v223
	v_sub_f32_e32 v224, v122, v224
	v_sub_f32_e32 v225, v122, v225
	v_sub_f32_e32 v226, v122, v226
	v_sub_f32_e32 v227, v122, v227
	v_sub_f32_e32 v228, v122, v228
	v_sub_f32_e32 v229, v122, v229
	v_mul_f32_e32 v214, 0x3fb8aa3b, v214
	v_mul_f32_e32 v215, 0x3fb8aa3b, v215
	v_mul_f32_e32 v216, 0x3fb8aa3b, v216
	v_mul_f32_e32 v217, 0x3fb8aa3b, v217
	v_mul_f32_e32 v218, 0x3fb8aa3b, v218
	v_mul_f32_e32 v219, 0x3fb8aa3b, v219
	v_mul_f32_e32 v220, 0x3fb8aa3b, v220
	v_mul_f32_e32 v221, 0x3fb8aa3b, v221
	v_mul_f32_e32 v222, 0x3fb8aa3b, v222
	v_mul_f32_e32 v223, 0x3fb8aa3b, v223
	v_mul_f32_e32 v224, 0x3fb8aa3b, v224
	v_mul_f32_e32 v225, 0x3fb8aa3b, v225
	v_mul_f32_e32 v226, 0x3fb8aa3b, v226
	v_mul_f32_e32 v227, 0x3fb8aa3b, v227
	v_mul_f32_e32 v228, 0x3fb8aa3b, v228
	v_mul_f32_e32 v229, 0x3fb8aa3b, v229
	v_exp_f32_e32 v214, v214
	v_exp_f32_e32 v215, v215
	v_exp_f32_e32 v216, v216
	v_exp_f32_e32 v217, v217
	v_exp_f32_e32 v218, v218
	v_exp_f32_e32 v219, v219
	v_exp_f32_e32 v220, v220
	v_exp_f32_e32 v221, v221
	v_exp_f32_e32 v222, v222
	v_exp_f32_e32 v223, v223
	v_exp_f32_e32 v224, v224
	v_exp_f32_e32 v225, v225
	v_exp_f32_e32 v226, v226
	v_exp_f32_e32 v227, v227
	v_exp_f32_e32 v228, v228
	v_exp_f32_e32 v229, v229
	v_mul_f32_e32 v214, v34, v214
	v_mul_f32_e32 v215, v35, v215
	v_mul_f32_e32 v216, v36, v216
	v_mul_f32_e32 v217, v37, v217
	v_mul_f32_e32 v218, v38, v218
	v_mul_f32_e32 v219, v39, v219
	v_mul_f32_e32 v220, v40, v220
	v_mul_f32_e32 v221, v41, v221
	v_mul_f32_e32 v222, v42, v222
	v_mul_f32_e32 v223, v43, v223
	v_mul_f32_e32 v224, v44, v224
	v_mul_f32_e32 v225, v45, v225
	v_mul_f32_e32 v226, v46, v226
	v_mul_f32_e32 v227, v47, v227
	v_mul_f32_e32 v228, v48, v228
	v_mul_f32_e32 v229, v49, v229
	v_cndmask_b32_e64 v214, 0, v214, s[18:19]
	v_cndmask_b32_e64 v215, 0, v215, s[20:21]
	v_cndmask_b32_e64 v216, 0, v216, s[22:23]
	v_cndmask_b32_e64 v217, 0, v217, s[24:25]
	v_cndmask_b32_e64 v218, 0, v218, s[26:27]
	v_cndmask_b32_e64 v219, 0, v219, s[28:29]
	v_cndmask_b32_e64 v220, 0, v220, s[30:31]
	v_cndmask_b32_e64 v221, 0, v221, s[34:35]
	v_cndmask_b32_e64 v222, 0, v222, s[36:37]
	v_cndmask_b32_e64 v223, 0, v223, s[38:39]
	v_cndmask_b32_e64 v224, 0, v224, s[40:41]
	v_cndmask_b32_e64 v225, 0, v225, s[42:43]
	v_cndmask_b32_e64 v226, 0, v226, s[44:45]
	v_cndmask_b32_e64 v227, 0, v227, s[46:47]
	v_cndmask_b32_e64 v228, 0, v228, s[48:49]
	v_cndmask_b32_e64 v229, 0, v229, s[50:51]
	v_cvt_pk_bf16_f32 v214, v214, s0
	v_cvt_pk_bf16_f32 v215, v215, s0
	v_cvt_pk_bf16_f32 v216, v216, s0
	v_cvt_pk_bf16_f32 v217, v217, s0
	v_cvt_pk_bf16_f32 v218, v218, s0
	v_cvt_pk_bf16_f32 v219, v219, s0
	v_cvt_pk_bf16_f32 v220, v220, s0
	v_cvt_pk_bf16_f32 v221, v221, s0
	v_cvt_pk_bf16_f32 v222, v222, s0
	v_cvt_pk_bf16_f32 v223, v223, s0
	v_cvt_pk_bf16_f32 v224, v224, s0
	v_cvt_pk_bf16_f32 v225, v225, s0
	v_cvt_pk_bf16_f32 v226, v226, s0
	v_cvt_pk_bf16_f32 v227, v227, s0
	v_cvt_pk_bf16_f32 v228, v228, s0
	v_cvt_pk_bf16_f32 v229, v229, s0
	ds_write_b16 v192, v214
	ds_write_b16 v192, v215 offset:144
	ds_write_b16 v192, v216 offset:288
	ds_write_b16 v192, v217 offset:432
	ds_write_b16 v192, v218 offset:1152
	ds_write_b16 v192, v219 offset:1296
	ds_write_b16 v192, v220 offset:1440
	ds_write_b16 v192, v221 offset:1584
	ds_write_b16 v192, v222 offset:2304
	ds_write_b16 v192, v223 offset:2448
	ds_write_b16 v192, v224 offset:2592
	ds_write_b16 v192, v225 offset:2736
	ds_write_b16 v192, v226 offset:3456
	ds_write_b16 v192, v227 offset:3600
	ds_write_b16 v192, v228 offset:3744
	ds_write_b16 v192, v229 offset:3888
	v_mov_b32_e32 v193, 0
	s_mov_b32 s70, 0
	v_mov_b32_e32 v122, v154

.LBB0_964:
	s_or_b64 exec, exec, s[6:7]
	v_lshl_or_b32 v134, v131, 5, v130
	v_lshlrev_b32_e32 v130, 2, v134
	s_waitcnt lgkmcnt(0)
	s_barrier
	global_load_dword v135, v130, s[44:45]
	global_load_dword v136, v130, s[44:45] offset:64
	v_lshl_add_u32 v143, v138, 2, v219
	ds_read_b128 v[150:153], v143
	ds_read_b128 v[154:157], v143 offset:16
	ds_read_b128 v[158:161], v143 offset:32
	ds_read_b128 v[162:165], v143 offset:48
	s_mov_b32 s2, 0x358637bd
	s_waitcnt lgkmcnt(3)
	v_mov_b32_e32 v131, v150
	s_waitcnt lgkmcnt(2)
	v_mov_b32_e32 v130, v154
	v_mov_b32_e32 v150, v155
	v_pk_add_f32 v[130:131], v[130:131], v[150:151]
	v_mov_b32_e32 v140, v156
	v_mov_b32_e32 v141, v152
	v_pk_add_f32 v[130:131], v[140:141], v[130:131]
	v_mov_b32_e32 v152, v157
	v_pk_add_f32 v[140:141], v[152:153], v[130:131]
	v_mov_b64_e32 v[130:131], s[2:3]
	v_pk_fma_f32 v[140:141], v[140:141], s[74:75], v[130:131] op_sel_hi:[1,0,0]
	s_waitcnt lgkmcnt(0)
	v_mov_b32_e32 v150, v164
	v_mul_f32_e32 v137, 0x4b800000, v141
	v_cmp_gt_f32_e64 s[6:7], s91, v141
	v_cmp_gt_f32_e32 vcc, s91, v140
	v_mov_b32_e32 v151, v160
	v_cndmask_b32_e64 v137, v141, v137, s[6:7]
	v_rsq_f32_e32 v137, v137
	v_mov_b32_e32 v141, v158
	v_mov_b32_e32 v158, v163
	v_mov_b32_e32 v160, v165
	v_mul_f32_e32 v138, 0x45800000, v137
	v_cndmask_b32_e64 v137, v137, v138, s[6:7]
	v_lshl_add_u32 v144, v144, 4, v219
	v_cvt_pk_bf16_f32 v59, v59, s0
	v_cvt_pk_bf16_f32 v58, v58, s0
	v_lshlrev_b32_e32 v59, 16, v59
	v_or_b32_sdwa v58, v59, v58 dst_sel:DWORD dst_unused:UNUSED_PAD src0_sel:DWORD src1_sel:WORD_0
	v_cvt_pk_bf16_f32 v59, v60, s0
	v_cvt_pk_bf16_f32 v60, v61, s0
	v_lshlrev_b32_e32 v60, 16, v60
	v_or_b32_sdwa v59, v60, v59 dst_sel:DWORD dst_unused:UNUSED_PAD src0_sel:DWORD src1_sel:WORD_0
	v_cvt_pk_bf16_f32 v51, v51, s0
	v_cvt_pk_bf16_f32 v50, v50, s0
	v_lshlrev_b32_e32 v51, 16, v51
	v_or_b32_sdwa v50, v51, v50 dst_sel:DWORD dst_unused:UNUSED_PAD src0_sel:DWORD src1_sel:WORD_0
	v_cvt_pk_bf16_f32 v51, v52, s0
	v_cvt_pk_bf16_f32 v52, v53, s0
	v_lshlrev_b32_e32 v52, 16, v52
	v_or_b32_sdwa v51, v52, v51 dst_sel:DWORD dst_unused:UNUSED_PAD src0_sel:DWORD src1_sel:WORD_0
	v_cvt_pk_bf16_f32 v43, v43, s0
	v_cvt_pk_bf16_f32 v42, v42, s0
	v_lshlrev_b32_e32 v43, 16, v43
	v_or_b32_sdwa v42, v43, v42 dst_sel:DWORD dst_unused:UNUSED_PAD src0_sel:DWORD src1_sel:WORD_0
	v_cvt_pk_bf16_f32 v43, v44, s0
	v_cvt_pk_bf16_f32 v44, v45, s0
	v_lshlrev_b32_e32 v44, 16, v44
	v_or_b32_sdwa v43, v44, v43 dst_sel:DWORD dst_unused:UNUSED_PAD src0_sel:DWORD src1_sel:WORD_0
	v_cvt_pk_bf16_f32 v35, v35, s0
	v_cvt_pk_bf16_f32 v34, v34, s0
	v_lshlrev_b32_e32 v35, 16, v35
	v_or_b32_sdwa v34, v35, v34 dst_sel:DWORD dst_unused:UNUSED_PAD src0_sel:DWORD src1_sel:WORD_0
	v_cvt_pk_bf16_f32 v35, v36, s0
	v_cvt_pk_bf16_f32 v36, v37, s0
	v_lshlrev_b32_e32 v36, 16, v36
	v_or_b32_sdwa v35, v36, v35 dst_sel:DWORD dst_unused:UNUSED_PAD src0_sel:DWORD src1_sel:WORD_0
	v_cvt_pk_bf16_f32 v27, v27, s0
	v_cvt_pk_bf16_f32 v26, v26, s0
	v_lshlrev_b32_e32 v27, 16, v27
	v_or_b32_sdwa v26, v27, v26 dst_sel:DWORD dst_unused:UNUSED_PAD src0_sel:DWORD src1_sel:WORD_0
	v_cvt_pk_bf16_f32 v27, v28, s0
	v_cvt_pk_bf16_f32 v28, v29, s0
	v_lshlrev_b32_e32 v28, 16, v28
	v_or_b32_sdwa v27, v28, v27 dst_sel:DWORD dst_unused:UNUSED_PAD src0_sel:DWORD src1_sel:WORD_0
	v_cvt_pk_bf16_f32 v19, v19, s0
	v_cvt_pk_bf16_f32 v18, v18, s0
	v_lshlrev_b32_e32 v19, 16, v19
	v_or_b32_sdwa v18, v19, v18 dst_sel:DWORD dst_unused:UNUSED_PAD src0_sel:DWORD src1_sel:WORD_0
	v_cvt_pk_bf16_f32 v19, v20, s0
	v_cvt_pk_bf16_f32 v20, v21, s0
	v_lshlrev_b32_e32 v20, 16, v20
	v_or_b32_sdwa v19, v20, v19 dst_sel:DWORD dst_unused:UNUSED_PAD src0_sel:DWORD src1_sel:WORD_0
	v_cvt_pk_bf16_f32 v11, v11, s0
	v_cvt_pk_bf16_f32 v10, v10, s0
	v_lshlrev_b32_e32 v11, 16, v11
	v_or_b32_sdwa v10, v11, v10 dst_sel:DWORD dst_unused:UNUSED_PAD src0_sel:DWORD src1_sel:WORD_0
	s_waitcnt vmcnt(0)
	v_mul_f32_e32 v138, v136, v137
	v_mul_f32_e32 v126, v126, v138
	v_mul_f32_e32 v138, 0x4b800000, v140
	v_cndmask_b32_e32 v138, v140, v138, vcc
	v_rsq_f32_e32 v138, v138
	v_cvt_pk_bf16_f32 v11, v12, s0
	v_cvt_pk_bf16_f32 v12, v13, s0
	v_lshlrev_b32_e32 v12, 16, v12
	v_mul_f32_e32 v140, 0x45800000, v138
	v_cndmask_b32_e32 v138, v138, v140, vcc
	v_mul_f32_e32 v140, v136, v138
	v_mul_f32_e32 v127, v127, v140
	v_mov_b32_e32 v140, v162
	v_pk_add_f32 v[140:141], v[140:141], v[158:159]
	v_or_b32_sdwa v11, v12, v11 dst_sel:DWORD dst_unused:UNUSED_PAD src0_sel:DWORD src1_sel:WORD_0
	v_pk_add_f32 v[140:141], v[150:151], v[140:141]
	v_cvt_pk_bf16_f32 v3, v3, s0
	v_pk_add_f32 v[140:141], v[160:161], v[140:141]
	v_cvt_pk_bf16_f32 v2, v2, s0
	v_pk_fma_f32 v[150:151], v[140:141], s[74:75], v[130:131] op_sel_hi:[1,0,0]
	v_lshlrev_b32_e32 v3, 16, v3
	v_mul_f32_e32 v140, 0x4b800000, v151
	v_cmp_gt_f32_e64 s[6:7], s91, v151
	v_cmp_gt_f32_e32 vcc, s91, v150
	v_or_b32_sdwa v2, v3, v2 dst_sel:DWORD dst_unused:UNUSED_PAD src0_sel:DWORD src1_sel:WORD_0
	v_cndmask_b32_e64 v140, v151, v140, s[6:7]
	v_rsq_f32_e32 v140, v140
	v_cvt_pk_bf16_f32 v3, v4, s0
	v_cvt_pk_bf16_f32 v4, v5, s0
	v_lshlrev_b32_e32 v4, 16, v4
	v_mul_f32_e32 v141, 0x45800000, v140
	v_cndmask_b32_e64 v140, v140, v141, s[6:7]
	v_mul_f32_e32 v141, v136, v140
	v_mul_f32_e32 v128, v128, v141
	v_mul_f32_e32 v141, 0x4b800000, v150
	v_cndmask_b32_e32 v141, v150, v141, vcc
	v_rsq_f32_e32 v141, v141
	v_or_b32_sdwa v3, v4, v3 dst_sel:DWORD dst_unused:UNUSED_PAD src0_sel:DWORD src1_sel:WORD_0
	v_mul_f32_e32 v150, 0x45800000, v141
	v_cndmask_b32_e32 v141, v141, v150, vcc
	v_mul_f32_e32 v150, v136, v141
	v_mul_f32_e32 v129, v129, v150
	ds_read_b128 v[150:153], v144
	ds_read_b128 v[154:157], v143 offset:272
	s_waitcnt lgkmcnt(1)
	v_mov_b32_e32 v159, v150
	s_waitcnt lgkmcnt(0)
	v_mov_b32_e32 v158, v154
	v_mov_b32_e32 v150, v155
	v_pk_add_f32 v[150:151], v[158:159], v[150:151]
	v_mov_b32_e32 v154, v156
	v_mov_b32_e32 v155, v152
	v_pk_add_f32 v[150:151], v[154:155], v[150:151]
	v_mov_b32_e32 v152, v157
	v_pk_add_f32 v[150:151], v[152:153], v[150:151]
	s_nop 0
	v_pk_fma_f32 v[150:151], v[150:151], s[74:75], v[130:131] op_sel_hi:[1,0,0]
	s_nop 0
	v_mul_f32_e32 v144, 0x4b800000, v151
	v_cmp_gt_f32_e64 s[6:7], s91, v151
	v_cmp_gt_f32_e32 vcc, s91, v150
	s_nop 0
	v_cndmask_b32_e64 v144, v151, v144, s[6:7]
	v_rsq_f32_e32 v144, v144
	s_nop 0
	v_mul_f32_e32 v151, 0x45800000, v144
	v_cndmask_b32_e64 v151, v144, v151, s[6:7]
	v_mul_f32_e32 v144, v135, v151
	v_mul_f32_e32 v144, v118, v144
	v_mul_f32_e32 v118, v136, v151
	v_mul_f32_e32 v118, v122, v118
	v_mul_f32_e32 v122, 0x4b800000, v150
	v_cndmask_b32_e32 v122, v150, v122, vcc
	v_rsq_f32_e32 v122, v122
	v_cvt_pk_bf16_f32 v118, v118, s0
	v_mul_f32_e32 v150, 0x45800000, v122
	v_cndmask_b32_e32 v150, v122, v150, vcc
	v_mul_f32_e32 v122, v135, v150
	v_mul_f32_e32 v122, v119, v122
	v_mul_f32_e32 v119, v136, v150
	ds_read_b128 v[150:153], v143 offset:288
	ds_read_b128 v[154:157], v143 offset:304
	v_mul_f32_e32 v119, v123, v119
	v_cvt_pk_bf16_f32 v122, v122, s0
	s_waitcnt lgkmcnt(1)
	v_mov_b32_e32 v159, v150
	s_waitcnt lgkmcnt(0)
	v_mov_b32_e32 v158, v154
	v_mov_b32_e32 v150, v155
	v_pk_add_f32 v[150:151], v[158:159], v[150:151]
	v_mov_b32_e32 v154, v156
	v_mov_b32_e32 v155, v152
	v_pk_add_f32 v[150:151], v[154:155], v[150:151]
	v_mov_b32_e32 v152, v157
	v_pk_add_f32 v[150:151], v[152:153], v[150:151]
	s_nop 0
	v_pk_fma_f32 v[150:151], v[150:151], s[74:75], v[130:131] op_sel_hi:[1,0,0]
	s_nop 0
	v_mul_f32_e32 v123, 0x4b800000, v151
	v_cmp_gt_f32_e64 s[6:7], s91, v151
	v_cmp_gt_f32_e32 vcc, s91, v150
	s_nop 0
	v_cndmask_b32_e64 v123, v151, v123, s[6:7]
	v_rsq_f32_e32 v123, v123
	s_nop 0
	v_mul_f32_e32 v151, 0x45800000, v123
	v_cndmask_b32_e64 v151, v123, v151, s[6:7]
	v_mul_f32_e32 v123, v135, v151
	v_mul_f32_e32 v123, v120, v123
	v_mul_f32_e32 v120, v136, v151
	v_mul_f32_e32 v120, v124, v120
	v_mul_f32_e32 v124, 0x4b800000, v150
	v_cndmask_b32_e32 v124, v150, v124, vcc
	v_rsq_f32_e32 v124, v124
	s_nop 0
	v_mul_f32_e32 v150, 0x45800000, v124
	v_cndmask_b32_e32 v150, v124, v150, vcc
	v_mul_f32_e32 v124, v135, v150
	v_mul_f32_e32 v124, v121, v124
	v_mul_f32_e32 v121, v136, v150
	v_mul_f32_e32 v121, v125, v121
	v_lshl_add_u32 v125, v149, 4, v219
	ds_read_b128 v[150:153], v125
	ds_read_b128 v[154:157], v143 offset:528
	v_cvt_pk_bf16_f32 v124, v124, s0
	s_waitcnt lgkmcnt(1)
	v_mov_b32_e32 v159, v150
	s_waitcnt lgkmcnt(0)
	v_mov_b32_e32 v158, v154
	v_mov_b32_e32 v150, v155
	v_pk_add_f32 v[150:151], v[158:159], v[150:151]
	v_mov_b32_e32 v154, v156
	v_mov_b32_e32 v155, v152
	v_pk_add_f32 v[150:151], v[154:155], v[150:151]
	v_mov_b32_e32 v152, v157
	v_pk_add_f32 v[150:151], v[152:153], v[150:151]
	s_nop 0
	v_pk_fma_f32 v[150:151], v[150:151], s[74:75], v[130:131] op_sel_hi:[1,0,0]
	s_nop 0
	v_mul_f32_e32 v125, 0x4b800000, v151
	v_cmp_gt_f32_e64 s[6:7], s91, v151
	v_cmp_gt_f32_e32 vcc, s91, v150
	s_nop 0
	v_cndmask_b32_e64 v125, v151, v125, s[6:7]
	v_rsq_f32_e32 v125, v125
	s_nop 0
	v_mul_f32_e32 v149, 0x45800000, v125
	v_cndmask_b32_e64 v149, v125, v149, s[6:7]
	v_mul_f32_e32 v125, v135, v149
	v_mul_f32_e32 v125, v110, v125
	v_mul_f32_e32 v110, v136, v149
	v_mul_f32_e32 v110, v114, v110
	v_mul_f32_e32 v114, 0x4b800000, v150
	v_cndmask_b32_e32 v114, v150, v114, vcc
	ds_read_b128 v[150:153], v143 offset:544
	ds_read_b128 v[154:157], v143 offset:560
	v_rsq_f32_e32 v114, v114
	v_cvt_pk_bf16_f32 v110, v110, s0
	s_waitcnt lgkmcnt(1)
	v_mov_b32_e32 v159, v150
	s_waitcnt lgkmcnt(0)
	v_mov_b32_e32 v158, v154
	v_mov_b32_e32 v150, v155
	v_mul_f32_e32 v149, 0x45800000, v114
	v_pk_add_f32 v[150:151], v[158:159], v[150:151]
	v_mov_b32_e32 v154, v156
	v_mov_b32_e32 v155, v152
	v_cndmask_b32_e32 v149, v114, v149, vcc
	v_pk_add_f32 v[150:151], v[154:155], v[150:151]
	v_mov_b32_e32 v152, v157
	v_mul_f32_e32 v114, v135, v149
	v_pk_add_f32 v[150:151], v[152:153], v[150:151]
	v_mul_f32_e32 v114, v111, v114
	v_mul_f32_e32 v111, v136, v149
	v_pk_fma_f32 v[150:151], v[150:151], s[74:75], v[130:131] op_sel_hi:[1,0,0]
	v_mul_f32_e32 v111, v115, v111
	v_mul_f32_e32 v115, 0x4b800000, v151
	v_cmp_gt_f32_e64 s[6:7], s91, v151
	v_cmp_gt_f32_e32 vcc, s91, v150
	v_cvt_pk_bf16_f32 v114, v114, s0
	v_cndmask_b32_e64 v115, v151, v115, s[6:7]
	v_rsq_f32_e32 v115, v115
	s_nop 0
	v_mul_f32_e32 v149, 0x45800000, v115
	v_cndmask_b32_e64 v149, v115, v149, s[6:7]
	v_mul_f32_e32 v115, v135, v149
	v_mul_f32_e32 v115, v112, v115
	v_mul_f32_e32 v112, v136, v149
	v_mul_f32_e32 v112, v116, v112
	v_mul_f32_e32 v116, 0x4b800000, v150
	v_cndmask_b32_e32 v116, v150, v116, vcc
	v_rsq_f32_e32 v116, v116
	s_nop 0
	v_mul_f32_e32 v149, 0x45800000, v116
	v_cndmask_b32_e32 v149, v116, v149, vcc
	v_mul_f32_e32 v116, v135, v149
	v_mul_f32_e32 v116, v113, v116
	v_mul_f32_e32 v113, v136, v149
	v_mul_f32_e32 v113, v117, v113
	v_lshl_add_u32 v117, v148, 4, v219
	ds_read_b128 v[148:151], v117
	ds_read_b128 v[152:155], v143 offset:784
	v_cvt_pk_bf16_f32 v116, v116, s0
	s_waitcnt lgkmcnt(1)
	v_mov_b32_e32 v157, v148
	s_waitcnt lgkmcnt(0)
	v_mov_b32_e32 v156, v152
	v_mov_b32_e32 v148, v153
	v_pk_add_f32 v[148:149], v[156:157], v[148:149]
	v_mov_b32_e32 v152, v154
	v_mov_b32_e32 v153, v150
	v_pk_add_f32 v[148:149], v[152:153], v[148:149]
	v_mov_b32_e32 v150, v155
	v_pk_add_f32 v[148:149], v[150:151], v[148:149]
	s_nop 0
	v_pk_fma_f32 v[148:149], v[148:149], s[74:75], v[130:131] op_sel_hi:[1,0,0]
	s_nop 0
	v_mul_f32_e32 v117, 0x4b800000, v149
	v_cmp_gt_f32_e64 s[6:7], s91, v149
	v_cmp_gt_f32_e32 vcc, s91, v148
	s_nop 0
	v_cndmask_b32_e64 v117, v149, v117, s[6:7]
	v_rsq_f32_e32 v117, v117
	s_nop 0
	v_mul_f32_e32 v149, 0x45800000, v117
	v_cndmask_b32_e64 v149, v117, v149, s[6:7]
	v_mul_f32_e32 v117, v135, v149
	v_mul_f32_e32 v117, v102, v117
	v_mul_f32_e32 v102, v136, v149
	v_mul_f32_e32 v102, v106, v102
	v_mul_f32_e32 v106, 0x4b800000, v148
	v_cndmask_b32_e32 v106, v148, v106, vcc
	v_rsq_f32_e32 v106, v106
	v_cvt_pk_bf16_f32 v102, v102, s0
	v_mul_f32_e32 v148, 0x45800000, v106
	v_cndmask_b32_e32 v148, v106, v148, vcc
	v_mul_f32_e32 v106, v135, v148
	v_mul_f32_e32 v106, v103, v106
	v_mul_f32_e32 v103, v136, v148
	ds_read_b128 v[148:151], v143 offset:800
	ds_read_b128 v[152:155], v143 offset:816
	v_mul_f32_e32 v103, v107, v103
	v_cvt_pk_bf16_f32 v106, v106, s0
	s_waitcnt lgkmcnt(1)
	v_mov_b32_e32 v157, v148
	s_waitcnt lgkmcnt(0)
	v_mov_b32_e32 v156, v152
	v_mov_b32_e32 v148, v153
	v_pk_add_f32 v[148:149], v[156:157], v[148:149]
	v_mov_b32_e32 v152, v154
	v_mov_b32_e32 v153, v150
	v_pk_add_f32 v[148:149], v[152:153], v[148:149]
	v_mov_b32_e32 v150, v155
	v_pk_add_f32 v[148:149], v[150:151], v[148:149]
	s_nop 0
	v_pk_fma_f32 v[148:149], v[148:149], s[74:75], v[130:131] op_sel_hi:[1,0,0]
	s_nop 0
	v_mul_f32_e32 v107, 0x4b800000, v149
	v_cmp_gt_f32_e64 s[6:7], s91, v149
	v_cmp_gt_f32_e32 vcc, s91, v148
	s_nop 0
	v_cndmask_b32_e64 v107, v149, v107, s[6:7]
	v_rsq_f32_e32 v107, v107
	s_nop 0
	v_mul_f32_e32 v149, 0x45800000, v107
	v_cndmask_b32_e64 v149, v107, v149, s[6:7]
	v_mul_f32_e32 v107, v135, v149
	v_mul_f32_e32 v107, v104, v107
	v_mul_f32_e32 v104, v136, v149
	v_mul_f32_e32 v104, v108, v104
	v_mul_f32_e32 v108, 0x4b800000, v148
	v_cndmask_b32_e32 v108, v148, v108, vcc
	v_rsq_f32_e32 v108, v108
	v_cvt_pk_bf16_f32 v104, v104, s0
	v_mul_f32_e32 v148, 0x45800000, v108
	v_cndmask_b32_e32 v148, v108, v148, vcc
	v_mul_f32_e32 v108, v135, v148
	v_mul_f32_e32 v108, v105, v108
	v_mul_f32_e32 v105, v136, v148
	v_mul_f32_e32 v105, v109, v105
	v_lshl_add_u32 v109, v147, 4, v219
	ds_read_b128 v[148:151], v109
	ds_read_b128 v[152:155], v143 offset:2064
	v_cvt_pk_bf16_f32 v108, v108, s0
	s_waitcnt lgkmcnt(1)
	v_mov_b32_e32 v157, v148
	s_waitcnt lgkmcnt(0)
	v_mov_b32_e32 v156, v152
	v_mov_b32_e32 v148, v153
	v_pk_add_f32 v[148:149], v[156:157], v[148:149]
	v_mov_b32_e32 v152, v154
	v_mov_b32_e32 v153, v150
	v_pk_add_f32 v[148:149], v[152:153], v[148:149]
	v_mov_b32_e32 v150, v155
	v_pk_add_f32 v[148:149], v[150:151], v[148:149]
	s_nop 0
	v_pk_fma_f32 v[148:149], v[148:149], s[74:75], v[130:131] op_sel_hi:[1,0,0]
	s_nop 0
	v_mul_f32_e32 v109, 0x4b800000, v149
	v_cmp_gt_f32_e64 s[6:7], s91, v149
	v_cmp_gt_f32_e32 vcc, s91, v148
	s_nop 0
	v_cndmask_b32_e64 v109, v149, v109, s[6:7]
	v_rsq_f32_e32 v109, v109
	s_nop 0
	v_mul_f32_e32 v147, 0x45800000, v109
	v_cndmask_b32_e64 v147, v109, v147, s[6:7]
	v_mul_f32_e32 v109, v135, v147
	v_mul_f32_e32 v109, v94, v109
	v_mul_f32_e32 v94, v136, v147
	v_mul_f32_e32 v94, v98, v94
	v_mul_f32_e32 v98, 0x4b800000, v148
	v_cndmask_b32_e32 v98, v148, v98, vcc
	ds_read_b128 v[148:151], v143 offset:2080
	ds_read_b128 v[152:155], v143 offset:2096
	v_rsq_f32_e32 v98, v98
	s_waitcnt lgkmcnt(1)
	v_mov_b32_e32 v157, v148
	s_waitcnt lgkmcnt(0)
	v_mov_b32_e32 v156, v152
	v_mov_b32_e32 v148, v153
	v_mul_f32_e32 v147, 0x45800000, v98
	v_pk_add_f32 v[148:149], v[156:157], v[148:149]
	v_mov_b32_e32 v152, v154
	v_mov_b32_e32 v153, v150
	v_cndmask_b32_e32 v147, v98, v147, vcc
	v_pk_add_f32 v[148:149], v[152:153], v[148:149]
	v_mov_b32_e32 v150, v155
	v_mul_f32_e32 v98, v135, v147
	v_pk_add_f32 v[148:149], v[150:151], v[148:149]
	v_mul_f32_e32 v98, v95, v98
	v_mul_f32_e32 v95, v136, v147
	v_pk_fma_f32 v[148:149], v[148:149], s[74:75], v[130:131] op_sel_hi:[1,0,0]
	v_mul_f32_e32 v95, v99, v95
	v_mul_f32_e32 v99, 0x4b800000, v149
	v_cmp_gt_f32_e64 s[6:7], s91, v149
	v_cmp_gt_f32_e32 vcc, s91, v148
	s_nop 0
	v_cndmask_b32_e64 v99, v149, v99, s[6:7]
	v_rsq_f32_e32 v99, v99
	s_nop 0
	v_mul_f32_e32 v147, 0x45800000, v99
	v_cndmask_b32_e64 v147, v99, v147, s[6:7]
	v_mul_f32_e32 v99, v135, v147
	v_mul_f32_e32 v99, v96, v99
	v_mul_f32_e32 v96, v136, v147
	v_mul_f32_e32 v96, v100, v96
	v_mul_f32_e32 v100, 0x4b800000, v148
	v_cndmask_b32_e32 v100, v148, v100, vcc
	v_rsq_f32_e32 v100, v100
	s_nop 0
	v_mul_f32_e32 v147, 0x45800000, v100
	v_cndmask_b32_e32 v147, v100, v147, vcc
	v_mul_f32_e32 v100, v135, v147
	v_mul_f32_e32 v100, v97, v100
	v_mul_f32_e32 v97, v136, v147
	v_mul_f32_e32 v97, v101, v97
	v_lshl_add_u32 v101, v146, 4, v219
	ds_read_b128 v[146:149], v101
	ds_read_b128 v[150:153], v143 offset:2320
	s_waitcnt lgkmcnt(1)
	v_mov_b32_e32 v155, v146
	s_waitcnt lgkmcnt(0)
	v_mov_b32_e32 v154, v150
	v_mov_b32_e32 v146, v151
	v_pk_add_f32 v[146:147], v[154:155], v[146:147]
	v_mov_b32_e32 v150, v152
	v_mov_b32_e32 v151, v148
	v_pk_add_f32 v[146:147], v[150:151], v[146:147]
	v_mov_b32_e32 v148, v153
	v_pk_add_f32 v[146:147], v[148:149], v[146:147]
	s_nop 0
	v_pk_fma_f32 v[146:147], v[146:147], s[74:75], v[130:131] op_sel_hi:[1,0,0]
	s_nop 0
	v_mul_f32_e32 v101, 0x4b800000, v147
	v_cmp_gt_f32_e64 s[6:7], s91, v147
	v_cmp_gt_f32_e32 vcc, s91, v146
	s_nop 0
	v_cndmask_b32_e64 v101, v147, v101, s[6:7]
	v_rsq_f32_e32 v101, v101
	s_nop 0
	v_mul_f32_e32 v147, 0x45800000, v101
	v_cndmask_b32_e64 v147, v101, v147, s[6:7]
	v_mul_f32_e32 v101, v135, v147
	v_mul_f32_e32 v101, v86, v101
	v_mul_f32_e32 v86, v136, v147
	v_mul_f32_e32 v86, v90, v86
	v_mul_f32_e32 v90, 0x4b800000, v146
	v_cndmask_b32_e32 v90, v146, v90, vcc
	v_rsq_f32_e32 v90, v90
	s_nop 0
	v_mul_f32_e32 v146, 0x45800000, v90
	v_cndmask_b32_e32 v146, v90, v146, vcc
	v_mul_f32_e32 v90, v135, v146
	v_mul_f32_e32 v90, v87, v90
	v_mul_f32_e32 v87, v136, v146
	ds_read_b128 v[146:149], v143 offset:2336
	ds_read_b128 v[150:153], v143 offset:2352
	v_mul_f32_e32 v87, v91, v87
	s_waitcnt lgkmcnt(1)
	v_mov_b32_e32 v155, v146
	s_waitcnt lgkmcnt(0)
	v_mov_b32_e32 v154, v150
	v_mov_b32_e32 v146, v151
	v_pk_add_f32 v[146:147], v[154:155], v[146:147]
	v_mov_b32_e32 v150, v152
	v_mov_b32_e32 v151, v148
	v_pk_add_f32 v[146:147], v[150:151], v[146:147]
	v_mov_b32_e32 v148, v153
	v_pk_add_f32 v[146:147], v[148:149], v[146:147]
	s_nop 0
	v_pk_fma_f32 v[146:147], v[146:147], s[74:75], v[130:131] op_sel_hi:[1,0,0]
	s_nop 0
	v_mul_f32_e32 v91, 0x4b800000, v147
	v_cmp_gt_f32_e64 s[6:7], s91, v147
	v_cmp_gt_f32_e32 vcc, s91, v146
	s_nop 0
	v_cndmask_b32_e64 v91, v147, v91, s[6:7]
	v_rsq_f32_e32 v91, v91
	s_nop 0
	v_mul_f32_e32 v147, 0x45800000, v91
	v_cndmask_b32_e64 v147, v91, v147, s[6:7]
	v_mul_f32_e32 v91, v135, v147
	v_mul_f32_e32 v91, v88, v91
	v_mul_f32_e32 v88, v136, v147
	v_mul_f32_e32 v88, v92, v88
	v_mul_f32_e32 v92, 0x4b800000, v146
	v_cndmask_b32_e32 v92, v146, v92, vcc
	v_rsq_f32_e32 v92, v92
	s_nop 0
	v_mul_f32_e32 v146, 0x45800000, v92
	v_cndmask_b32_e32 v146, v92, v146, vcc
	v_mul_f32_e32 v92, v135, v146
	v_mul_f32_e32 v92, v89, v92
	v_mul_f32_e32 v89, v136, v146
	v_mul_f32_e32 v89, v93, v89
	v_lshl_add_u32 v93, v145, 4, v219
	ds_read_b128 v[146:149], v93
	ds_read_b128 v[150:153], v143 offset:2576
	s_waitcnt lgkmcnt(1)
	v_mov_b32_e32 v155, v146
	s_waitcnt lgkmcnt(0)
	v_mov_b32_e32 v154, v150
	v_mov_b32_e32 v146, v151
	v_pk_add_f32 v[146:147], v[154:155], v[146:147]
	v_mov_b32_e32 v150, v152
	v_mov_b32_e32 v151, v148
	v_pk_add_f32 v[146:147], v[150:151], v[146:147]
	v_mov_b32_e32 v148, v153
	v_pk_add_f32 v[146:147], v[148:149], v[146:147]
	s_nop 0
	v_pk_fma_f32 v[146:147], v[146:147], s[74:75], v[130:131] op_sel_hi:[1,0,0]
	s_nop 0
	v_mul_f32_e32 v93, 0x4b800000, v147
	v_cmp_gt_f32_e64 s[6:7], s91, v147
	v_cmp_gt_f32_e32 vcc, s91, v146
	s_nop 0
	v_cndmask_b32_e64 v93, v147, v93, s[6:7]
	v_rsq_f32_e32 v93, v93
	s_nop 0
	v_mul_f32_e32 v145, 0x45800000, v93
	v_cndmask_b32_e64 v145, v93, v145, s[6:7]
	v_mul_f32_e32 v93, v135, v145
	v_mul_f32_e32 v93, v78, v93
	v_mul_f32_e32 v78, v136, v145
	v_mul_f32_e32 v78, v82, v78
	v_mul_f32_e32 v82, 0x4b800000, v146
	v_cndmask_b32_e32 v82, v146, v82, vcc
	ds_read_b128 v[146:149], v143 offset:2592
	ds_read_b128 v[150:153], v143 offset:2608
	v_rsq_f32_e32 v82, v82
	s_waitcnt lgkmcnt(1)
	v_mov_b32_e32 v155, v146
	s_waitcnt lgkmcnt(0)
	v_mov_b32_e32 v154, v150
	v_mov_b32_e32 v146, v151
	v_mul_f32_e32 v145, 0x45800000, v82
	v_pk_add_f32 v[146:147], v[154:155], v[146:147]
	v_mov_b32_e32 v150, v152
	v_mov_b32_e32 v151, v148
	v_cndmask_b32_e32 v145, v82, v145, vcc
	v_pk_add_f32 v[146:147], v[150:151], v[146:147]
	v_mov_b32_e32 v148, v153
	v_mul_f32_e32 v82, v135, v145
	v_pk_add_f32 v[146:147], v[148:149], v[146:147]
	v_mul_f32_e32 v82, v79, v82
	v_mul_f32_e32 v79, v136, v145
	v_pk_fma_f32 v[146:147], v[146:147], s[74:75], v[130:131] op_sel_hi:[1,0,0]
	v_mul_f32_e32 v79, v83, v79
	v_mul_f32_e32 v83, 0x4b800000, v147
	v_cmp_gt_f32_e64 s[6:7], s91, v147
	v_cmp_gt_f32_e32 vcc, s91, v146
	s_nop 0
	v_cndmask_b32_e64 v83, v147, v83, s[6:7]
	v_rsq_f32_e32 v83, v83
	s_nop 0
	v_mul_f32_e32 v145, 0x45800000, v83
	v_cndmask_b32_e64 v145, v83, v145, s[6:7]
	v_mul_f32_e32 v83, v135, v145
	v_mul_f32_e32 v83, v80, v83
	v_mul_f32_e32 v80, v136, v145
	v_mul_f32_e32 v80, v84, v80
	v_mul_f32_e32 v84, 0x4b800000, v146
	v_cndmask_b32_e32 v84, v146, v84, vcc
	v_rsq_f32_e32 v84, v84
	s_nop 0
	v_mul_f32_e32 v145, 0x45800000, v84
	v_cndmask_b32_e32 v145, v84, v145, vcc
	v_mul_f32_e32 v84, v135, v145
	v_mul_f32_e32 v84, v81, v84
	v_mul_f32_e32 v81, v136, v145
	v_mul_f32_e32 v81, v85, v81
	v_lshl_add_u32 v85, v142, 4, v219
	ds_read_b128 v[146:149], v85
	ds_read_b128 v[150:153], v143 offset:2832
	s_waitcnt lgkmcnt(1)
	v_mov_b32_e32 v155, v146
	s_waitcnt lgkmcnt(0)
	v_mov_b32_e32 v154, v150
	v_mov_b32_e32 v146, v151
	v_pk_add_f32 v[146:147], v[154:155], v[146:147]
	v_mov_b32_e32 v150, v152
	v_mov_b32_e32 v151, v148
	v_pk_add_f32 v[146:147], v[150:151], v[146:147]
	v_mov_b32_e32 v148, v153
	v_pk_add_f32 v[146:147], v[148:149], v[146:147]
	s_nop 0
	v_pk_fma_f32 v[146:147], v[146:147], s[74:75], v[130:131] op_sel_hi:[1,0,0]
	s_nop 0
	v_mul_f32_e32 v85, 0x4b800000, v147
	v_cmp_gt_f32_e64 s[6:7], s91, v147
	v_cmp_gt_f32_e32 vcc, s91, v146
	s_nop 0
	v_cndmask_b32_e64 v85, v147, v85, s[6:7]
	v_rsq_f32_e32 v85, v85
	s_nop 0
	v_mul_f32_e32 v142, 0x45800000, v85
	v_cndmask_b32_e64 v142, v85, v142, s[6:7]
	v_mul_f32_e32 v85, v135, v142
	v_mul_f32_e32 v85, v70, v85
	v_mul_f32_e32 v70, v136, v142
	v_mul_f32_e32 v74, v74, v70
	v_mul_f32_e32 v70, 0x4b800000, v146
	v_cndmask_b32_e32 v70, v146, v70, vcc
	v_rsq_f32_e32 v70, v70
	ds_read_b128 v[146:149], v143 offset:2848
	v_mul_f32_e32 v142, 0x45800000, v70
	v_cndmask_b32_e32 v70, v70, v142, vcc
	v_mul_f32_e32 v142, v135, v70
	v_mul_f32_e32 v70, v136, v70
	v_mul_f32_e32 v142, v71, v142
	v_mul_f32_e32 v71, v75, v70
	v_lshl_add_u32 v70, v139, 2, v219
	ds_read_b128 v[150:153], v70
	s_waitcnt lgkmcnt(1)
	v_mov_b32_e32 v155, v146
	s_waitcnt lgkmcnt(0)
	v_mov_b32_e32 v154, v150
	v_mov_b32_e32 v146, v151
	v_pk_add_f32 v[146:147], v[154:155], v[146:147]
	v_mov_b32_e32 v150, v152
	v_mov_b32_e32 v151, v148
	v_pk_add_f32 v[146:147], v[150:151], v[146:147]
	v_mov_b32_e32 v148, v153
	v_pk_add_f32 v[146:147], v[148:149], v[146:147]
	s_nop 0
	v_pk_fma_f32 v[146:147], v[146:147], s[74:75], v[130:131] op_sel_hi:[1,0,0]
	s_nop 0
	v_mul_f32_e32 v70, 0x4b800000, v147
	v_cmp_gt_f32_e64 s[6:7], s91, v147
	v_cmp_gt_f32_e32 vcc, s91, v146
	s_nop 0
	v_cndmask_b32_e64 v70, v147, v70, s[6:7]
	v_rsq_f32_e32 v70, v70
	s_nop 0
	v_mul_f32_e32 v75, 0x45800000, v70
	v_cndmask_b32_e64 v70, v70, v75, s[6:7]
	v_mul_f32_e32 v75, v135, v70
	v_mul_f32_e32 v70, v136, v70
	v_mul_f32_e32 v130, v72, v75
	v_mul_f32_e32 v75, v76, v70
	v_mul_f32_e32 v70, 0x4b800000, v146
	v_cndmask_b32_e32 v70, v146, v70, vcc
	v_rsq_f32_e32 v70, v70
	s_nop 0
	v_mul_f32_e32 v72, 0x45800000, v70
	v_cndmask_b32_e32 v70, v70, v72, vcc
	v_mul_f32_e32 v72, v135, v70
	v_mul_f32_e32 v70, v136, v70
	v_mul_f32_e32 v76, v73, v72
	v_mul_f32_e32 v73, v77, v70
	v_lshl_add_u32 v77, s16, 8, v0
	v_mul_f32_e32 v0, v135, v137
	v_mul_f32_e32 v0, v66, v0
	v_cvt_pk_bf16_f32 v66, v0, s0
	v_mul_f32_e32 v0, v135, v138
	v_or_b32_e32 v70, v77, v133
	v_mul_f32_e32 v137, v67, v0
	v_mul_f32_e32 v0, v135, v140
	v_lshlrev_b32_e32 v72, 10, v70
	v_mul_f32_e32 v138, v68, v0
	v_mul_f32_e32 v0, v135, v141
	v_lshl_or_b32 v67, s14, 7, v134
	v_or_b32_e32 v131, 0x400, v72
	v_mul_f32_e32 v135, v69, v0
	v_add_u32_e32 v0, v67, v72
	v_or_b32_e32 v133, 0x800, v72
	v_lshl_add_u64 v[68:69], v[0:1], 1, s[8:9]
	v_add_u32_e32 v0, v131, v67
	v_or_b32_e32 v136, 0xc00, v72
	global_store_short v[68:69], v66, off
	v_cvt_pk_bf16_f32 v66, v137, s0
	v_lshl_add_u64 v[68:69], v[0:1], 1, s[8:9]
	v_add_u32_e32 v0, v133, v67
	global_store_short v[68:69], v66, off
	v_cvt_pk_bf16_f32 v66, v138, s0
	v_lshl_add_u64 v[68:69], v[0:1], 1, s[8:9]
	v_add_u32_e32 v0, v136, v67
	global_store_short v[68:69], v66, off
	v_cvt_pk_bf16_f32 v66, v135, s0
	v_lshl_add_u64 v[68:69], v[0:1], 1, s[8:9]
	global_store_short v[68:69], v66, off
	v_or_b32_e32 v69, 16, v67
	v_add_u32_e32 v0, v69, v72
	v_cvt_pk_bf16_f32 v66, v126, s0
	v_lshl_add_u64 v[134:135], v[0:1], 1, s[8:9]
	v_add_u32_e32 v0, v69, v131
	global_store_short v[134:135], v66, off
	v_cvt_pk_bf16_f32 v66, v127, s0
	v_lshl_add_u64 v[126:127], v[0:1], 1, s[8:9]
	v_add_u32_e32 v0, v69, v133
	global_store_short v[126:127], v66, off
	v_cvt_pk_bf16_f32 v66, v128, s0
	v_lshl_add_u64 v[126:127], v[0:1], 1, s[8:9]
	v_add_u32_e32 v0, v69, v136
	global_store_short v[126:127], v66, off
	v_cvt_pk_bf16_f32 v66, v129, s0
	v_lshl_add_u64 v[126:127], v[0:1], 1, s[8:9]
	v_or_b32_e32 v72, 16, v70
	global_store_short v[126:127], v66, off
	v_lshlrev_b32_e32 v66, 10, v72
	v_or_b32_e32 v68, 0x400, v66
	v_add_u32_e32 v0, v66, v67
	v_or_b32_e32 v128, 0x800, v66
	v_cvt_pk_bf16_f32 v131, v144, s0
	v_lshl_add_u64 v[126:127], v[0:1], 1, s[8:9]
	v_add_u32_e32 v0, v68, v67
	v_or_b32_e32 v129, 0xc00, v66
	global_store_short v[126:127], v131, off
	v_lshl_add_u64 v[126:127], v[0:1], 1, s[8:9]
	v_add_u32_e32 v0, v128, v67
	global_store_short v[126:127], v122, off
	v_cvt_pk_bf16_f32 v126, v123, s0
	v_lshl_add_u64 v[122:123], v[0:1], 1, s[8:9]
	v_add_u32_e32 v0, v129, v67
	global_store_short v[122:123], v126, off
	v_lshl_add_u64 v[122:123], v[0:1], 1, s[8:9]
	v_add_u32_e32 v0, v69, v66
	global_store_short v[122:123], v124, off
	v_lshl_add_u64 v[122:123], v[0:1], 1, s[8:9]
	v_add_u32_e32 v0, v68, v69
	global_store_short v[122:123], v118, off
	v_cvt_pk_bf16_f32 v66, v119, s0
	v_lshl_add_u64 v[118:119], v[0:1], 1, s[8:9]
	v_add_u32_e32 v0, v128, v69
	global_store_short v[118:119], v66, off
	v_cvt_pk_bf16_f32 v66, v120, s0
	v_lshl_add_u64 v[118:119], v[0:1], 1, s[8:9]
	v_add_u32_e32 v0, v129, v69
	global_store_short v[118:119], v66, off
	v_cvt_pk_bf16_f32 v66, v121, s0
	v_lshl_add_u64 v[118:119], v[0:1], 1, s[8:9]
	v_or_b32_e32 v68, 32, v70
	global_store_short v[118:119], v66, off
	v_lshlrev_b32_e32 v66, 10, v68
	v_or_b32_e32 v120, 0x400, v66
	v_add_u32_e32 v0, v66, v67
	v_or_b32_e32 v121, 0x800, v66
	v_cvt_pk_bf16_f32 v123, v125, s0
	v_lshl_add_u64 v[118:119], v[0:1], 1, s[8:9]
	v_add_u32_e32 v0, v120, v67
	v_or_b32_e32 v122, 0xc00, v66
	global_store_short v[118:119], v123, off
	v_lshl_add_u64 v[118:119], v[0:1], 1, s[8:9]
	v_add_u32_e32 v0, v121, v67
	global_store_short v[118:119], v114, off
	v_cvt_pk_bf16_f32 v118, v115, s0
	v_lshl_add_u64 v[114:115], v[0:1], 1, s[8:9]
	v_add_u32_e32 v0, v122, v67
	global_store_short v[114:115], v118, off
	v_lshl_add_u64 v[114:115], v[0:1], 1, s[8:9]
	v_add_u32_e32 v0, v69, v66
	global_store_short v[114:115], v116, off
	v_lshl_add_u64 v[114:115], v[0:1], 1, s[8:9]
	v_add_u32_e32 v0, v120, v69
	global_store_short v[114:115], v110, off
	v_cvt_pk_bf16_f32 v66, v111, s0
	v_lshl_add_u64 v[110:111], v[0:1], 1, s[8:9]
	v_add_u32_e32 v0, v121, v69
	global_store_short v[110:111], v66, off
	v_cvt_pk_bf16_f32 v66, v112, s0
	v_lshl_add_u64 v[110:111], v[0:1], 1, s[8:9]
	v_add_u32_e32 v0, v122, v69
	global_store_short v[110:111], v66, off
	v_cvt_pk_bf16_f32 v66, v113, s0
	v_lshl_add_u64 v[110:111], v[0:1], 1, s[8:9]
	global_store_short v[110:111], v66, off
	v_or_b32_e32 v66, 48, v70
	v_lshlrev_b32_e32 v112, 10, v66
	v_or_b32_e32 v113, 0x400, v112
	v_add_u32_e32 v0, v112, v67
	v_or_b32_e32 v114, 0x800, v112
	v_cvt_pk_bf16_f32 v116, v117, s0
	v_lshl_add_u64 v[110:111], v[0:1], 1, s[8:9]
	v_add_u32_e32 v0, v113, v67
	v_or_b32_e32 v115, 0xc00, v112
	global_store_short v[110:111], v116, off
	v_lshl_add_u64 v[110:111], v[0:1], 1, s[8:9]
	v_add_u32_e32 v0, v114, v67
	global_store_short v[110:111], v106, off
	v_cvt_pk_bf16_f32 v110, v107, s0
	v_lshl_add_u64 v[106:107], v[0:1], 1, s[8:9]
	v_add_u32_e32 v0, v115, v67
	global_store_short v[106:107], v110, off
	v_lshl_add_u64 v[106:107], v[0:1], 1, s[8:9]
	v_add_u32_e32 v0, v69, v112
	global_store_short v[106:107], v108, off
	v_lshl_add_u64 v[106:107], v[0:1], 1, s[8:9]
	v_add_u32_e32 v0, v113, v69
	global_store_short v[106:107], v102, off
	v_cvt_pk_bf16_f32 v106, v103, s0
	v_lshl_add_u64 v[102:103], v[0:1], 1, s[8:9]
	v_add_u32_e32 v0, v114, v69
	global_store_short v[102:103], v106, off
	v_lshl_add_u64 v[102:103], v[0:1], 1, s[8:9]
	v_add_u32_e32 v0, v115, v69
	v_ashrrev_i32_e32 v77, 31, v77
	global_store_short v[102:103], v104, off
	v_lshl_add_u64 v[102:103], v[0:1], 1, s[8:9]
	v_cvt_pk_bf16_f32 v0, v62, s0
	v_add_u32_e32 v62, v70, v77
	v_cvt_pk_bf16_f32 v104, v105, s0
	v_xor_b32_e32 v62, v62, v77
	global_store_short v[102:103], v104, off
	v_mul_hi_u32 v103, v62, v132
	v_mul_lo_u32 v104, v103, s24
	v_sub_u32_e32 v62, v62, v104
	v_cmp_le_u32_e32 vcc, s24, v62
	v_add_u32_e32 v104, 1, v103
	v_xor_b32_e32 v102, s27, v77
	v_cndmask_b32_e32 v103, v103, v104, vcc
	v_subrev_u32_e32 v104, s24, v62
	v_cndmask_b32_e32 v62, v62, v104, vcc
	v_cmp_le_u32_e32 vcc, s24, v62
	v_add_u32_e32 v62, 1, v103
	s_nop 0
	v_cndmask_b32_e32 v62, v103, v62, vcc
	v_xor_b32_e32 v62, v62, v102
	v_sub_u32_e32 v103, v62, v102
	v_cvt_pk_bf16_f32 v62, v63, s0
	v_lshlrev_b32_e32 v62, 16, v62
	v_cvt_pk_bf16_f32 v63, v65, s0
	v_or_b32_sdwa v62, v62, v0 dst_sel:DWORD dst_unused:UNUSED_PAD src0_sel:DWORD src1_sel:WORD_0
	v_cvt_pk_bf16_f32 v0, v64, s0
	v_lshlrev_b32_e32 v63, 16, v63
	v_or_b32_sdwa v63, v63, v0 dst_sel:DWORD dst_unused:UNUSED_PAD src0_sel:DWORD src1_sel:WORD_0
	v_mul_lo_u32 v0, v103, s88
	v_add_u32_e32 v64, v0, v67
	v_add_u32_e32 v0, v0, v69
	v_mad_u64_u32 v[64:65], s[6:7], v64, s5, v[70:71]
	v_mad_u64_u32 v[60:61], s[6:7], v0, s5, v[70:71]
	v_and_b32_e32 v65, 0x78, v67
	v_lshlrev_b32_e32 v65, 4, v65
	v_xor_b32_e32 v64, v64, v65
	v_mov_b32_e32 v65, v1
	v_and_b32_e32 v61, 0x78, v69
	v_lshlrev_b32_e32 v61, 4, v61
	v_xor_b32_e32 v60, v60, v61
	v_mov_b32_e32 v61, v1
	v_cvt_pk_bf16_f32 v0, v54, s0
	v_add_u32_e32 v54, v72, v77
	v_lshl_add_u64 v[64:65], v[64:65], 1, s[10:11]
	v_lshl_add_u64 v[60:61], v[60:61], 1, s[10:11]
	v_xor_b32_e32 v54, v54, v77
	global_store_dwordx2 v[64:65], v[62:63], off
	global_store_dwordx2 v[60:61], v[58:59], off
	v_mul_hi_u32 v58, v54, v132
	v_mul_lo_u32 v59, v58, s24
	v_sub_u32_e32 v54, v54, v59
	v_cmp_le_u32_e32 vcc, s24, v54
	v_add_u32_e32 v59, 1, v58
	s_nop 0
	v_cndmask_b32_e32 v58, v58, v59, vcc
	v_subrev_u32_e32 v59, s24, v54
	v_cndmask_b32_e32 v54, v54, v59, vcc
	v_cmp_le_u32_e32 vcc, s24, v54
	v_add_u32_e32 v54, 1, v58
	s_nop 0
	v_cndmask_b32_e32 v54, v58, v54, vcc
	v_xor_b32_e32 v54, v54, v102
	v_sub_u32_e32 v58, v54, v102
	v_cvt_pk_bf16_f32 v54, v55, s0
	v_lshlrev_b32_e32 v54, 16, v54
	v_cvt_pk_bf16_f32 v55, v57, s0
	v_or_b32_sdwa v54, v54, v0 dst_sel:DWORD dst_unused:UNUSED_PAD src0_sel:DWORD src1_sel:WORD_0
	v_cvt_pk_bf16_f32 v0, v56, s0
	v_lshlrev_b32_e32 v55, 16, v55
	v_or_b32_sdwa v55, v55, v0 dst_sel:DWORD dst_unused:UNUSED_PAD src0_sel:DWORD src1_sel:WORD_0
	v_mul_lo_u32 v0, v58, s88
	v_add_u32_e32 v56, v0, v67
	v_add_u32_e32 v0, v0, v69
	v_mad_u64_u32 v[56:57], s[6:7], v56, s5, v[72:73]
	v_mad_u64_u32 v[52:53], s[6:7], v0, s5, v[72:73]
	v_and_b32_e32 v57, 0x78, v67
	v_lshlrev_b32_e32 v57, 4, v57
	v_xor_b32_e32 v56, v56, v57
	v_mov_b32_e32 v57, v1
	v_and_b32_e32 v53, 0x78, v69
	v_lshlrev_b32_e32 v53, 4, v53
	v_xor_b32_e32 v52, v52, v53
	v_mov_b32_e32 v53, v1
	v_cvt_pk_bf16_f32 v0, v46, s0
	v_add_u32_e32 v46, v68, v77
	v_lshl_add_u64 v[56:57], v[56:57], 1, s[10:11]
	v_lshl_add_u64 v[52:53], v[52:53], 1, s[10:11]
	v_xor_b32_e32 v46, v46, v77
	global_store_dwordx2 v[56:57], v[54:55], off
	global_store_dwordx2 v[52:53], v[50:51], off
	v_mul_hi_u32 v50, v46, v132
	v_mul_lo_u32 v51, v50, s24
	v_sub_u32_e32 v46, v46, v51
	v_cmp_le_u32_e32 vcc, s24, v46
	v_add_u32_e32 v51, 1, v50
	s_nop 0
	v_cndmask_b32_e32 v50, v50, v51, vcc
	v_subrev_u32_e32 v51, s24, v46
	v_cndmask_b32_e32 v46, v46, v51, vcc
	v_cmp_le_u32_e32 vcc, s24, v46
	v_add_u32_e32 v46, 1, v50
	s_nop 0
	v_cndmask_b32_e32 v46, v50, v46, vcc
	v_xor_b32_e32 v46, v46, v102
	v_sub_u32_e32 v50, v46, v102
	v_cvt_pk_bf16_f32 v46, v47, s0
	v_lshlrev_b32_e32 v46, 16, v46
	v_cvt_pk_bf16_f32 v47, v49, s0
	v_or_b32_sdwa v46, v46, v0 dst_sel:DWORD dst_unused:UNUSED_PAD src0_sel:DWORD src1_sel:WORD_0
	v_cvt_pk_bf16_f32 v0, v48, s0
	v_lshlrev_b32_e32 v47, 16, v47
	v_or_b32_sdwa v47, v47, v0 dst_sel:DWORD dst_unused:UNUSED_PAD src0_sel:DWORD src1_sel:WORD_0
	v_mul_lo_u32 v0, v50, s88
	v_add_u32_e32 v48, v0, v67
	v_add_u32_e32 v0, v0, v69
	v_mad_u64_u32 v[48:49], s[6:7], v48, s5, v[68:69]
	v_mad_u64_u32 v[44:45], s[6:7], v0, s5, v[68:69]
	v_and_b32_e32 v49, 0x78, v67
	v_lshlrev_b32_e32 v49, 4, v49
	v_xor_b32_e32 v48, v48, v49
	v_mov_b32_e32 v49, v1
	v_and_b32_e32 v45, 0x78, v69
	v_lshlrev_b32_e32 v45, 4, v45
	v_xor_b32_e32 v44, v44, v45
	v_mov_b32_e32 v45, v1
	v_cvt_pk_bf16_f32 v0, v38, s0
	v_add_u32_e32 v38, v66, v77
	v_lshl_add_u64 v[48:49], v[48:49], 1, s[10:11]
	v_lshl_add_u64 v[44:45], v[44:45], 1, s[10:11]
	v_xor_b32_e32 v38, v38, v77
	global_store_dwordx2 v[48:49], v[46:47], off
	global_store_dwordx2 v[44:45], v[42:43], off
	v_mul_hi_u32 v42, v38, v132
	v_mul_lo_u32 v43, v42, s24
	v_sub_u32_e32 v38, v38, v43
	v_cmp_le_u32_e32 vcc, s24, v38
	v_add_u32_e32 v43, 1, v42
	v_cvt_pk_bf16_f32 v44, v85, s0
	v_cndmask_b32_e32 v42, v42, v43, vcc
	v_subrev_u32_e32 v43, s24, v38
	v_cndmask_b32_e32 v38, v38, v43, vcc
	v_cmp_le_u32_e32 vcc, s24, v38
	v_add_u32_e32 v38, 1, v42
	v_cvt_pk_bf16_f32 v43, v93, s0
	v_cndmask_b32_e32 v38, v42, v38, vcc
	v_xor_b32_e32 v38, v38, v102
	v_sub_u32_e32 v42, v38, v102
	v_cvt_pk_bf16_f32 v38, v39, s0
	v_lshlrev_b32_e32 v38, 16, v38
	v_cvt_pk_bf16_f32 v39, v41, s0
	v_or_b32_sdwa v38, v38, v0 dst_sel:DWORD dst_unused:UNUSED_PAD src0_sel:DWORD src1_sel:WORD_0
	v_cvt_pk_bf16_f32 v0, v40, s0
	v_lshlrev_b32_e32 v39, 16, v39
	v_or_b32_sdwa v39, v39, v0 dst_sel:DWORD dst_unused:UNUSED_PAD src0_sel:DWORD src1_sel:WORD_0
	v_mul_lo_u32 v0, v42, s88
	v_add_u32_e32 v40, v0, v67
	v_mad_u64_u32 v[40:41], s[6:7], v40, s5, v[66:67]
	v_add_u32_e32 v0, v0, v69
	v_and_b32_e32 v41, 0x78, v67
	v_lshlrev_b32_e32 v41, 4, v41
	v_xor_b32_e32 v40, v40, v41
	v_mov_b32_e32 v41, v1
	v_mad_u64_u32 v[36:37], s[6:7], v0, s5, v[66:67]
	v_lshl_add_u64 v[40:41], v[40:41], 1, s[10:11]
	v_and_b32_e32 v37, 0x78, v69
	v_lshlrev_b32_e32 v37, 4, v37
	v_xor_b32_e32 v36, v36, v37
	v_mov_b32_e32 v37, v1
	global_store_dwordx2 v[40:41], v[38:39], off
	v_lshl_add_u64 v[36:37], v[36:37], 1, s[10:11]
	v_add_u32_e32 v40, 0x80, v70
	global_store_dwordx2 v[36:37], v[34:35], off
	v_lshlrev_b32_e32 v36, 10, v40
	v_or_b32_e32 v37, 0x400, v36
	v_add_u32_e32 v0, v36, v67
	v_or_b32_e32 v38, 0x800, v36
	v_cvt_pk_bf16_f32 v41, v109, s0
	v_lshl_add_u64 v[34:35], v[0:1], 1, s[8:9]
	v_add_u32_e32 v0, v37, v67
	v_or_b32_e32 v39, 0xc00, v36
	global_store_short v[34:35], v41, off
	v_cvt_pk_bf16_f32 v41, v98, s0
	v_lshl_add_u64 v[34:35], v[0:1], 1, s[8:9]
	v_add_u32_e32 v0, v38, v67
	global_store_short v[34:35], v41, off
	v_cvt_pk_bf16_f32 v41, v99, s0
	v_lshl_add_u64 v[34:35], v[0:1], 1, s[8:9]
	v_add_u32_e32 v0, v39, v67
	global_store_short v[34:35], v41, off
	v_cvt_pk_bf16_f32 v41, v100, s0
	v_lshl_add_u64 v[34:35], v[0:1], 1, s[8:9]
	v_add_u32_e32 v0, v69, v36
	global_store_short v[34:35], v41, off
	v_cvt_pk_bf16_f32 v41, v94, s0
	v_lshl_add_u64 v[34:35], v[0:1], 1, s[8:9]
	v_add_u32_e32 v0, v37, v69
	global_store_short v[34:35], v41, off
	v_cvt_pk_bf16_f32 v36, v95, s0
	v_lshl_add_u64 v[34:35], v[0:1], 1, s[8:9]
	v_add_u32_e32 v0, v38, v69
	global_store_short v[34:35], v36, off
	v_cvt_pk_bf16_f32 v36, v96, s0
	v_lshl_add_u64 v[34:35], v[0:1], 1, s[8:9]
	v_add_u32_e32 v0, v39, v69
	global_store_short v[34:35], v36, off
	v_cvt_pk_bf16_f32 v36, v97, s0
	v_lshl_add_u64 v[34:35], v[0:1], 1, s[8:9]
	v_add_u32_e32 v38, 0x90, v70
	global_store_short v[34:35], v36, off
	v_lshlrev_b32_e32 v36, 10, v38
	v_or_b32_e32 v37, 0x400, v36
	v_add_u32_e32 v0, v36, v67
	v_or_b32_e32 v39, 0x800, v36
	v_cvt_pk_bf16_f32 v42, v101, s0
	v_lshl_add_u64 v[34:35], v[0:1], 1, s[8:9]
	v_add_u32_e32 v0, v37, v67
	v_or_b32_e32 v41, 0xc00, v36
	global_store_short v[34:35], v42, off
	v_cvt_pk_bf16_f32 v42, v90, s0
	v_lshl_add_u64 v[34:35], v[0:1], 1, s[8:9]
	v_add_u32_e32 v0, v39, v67
	global_store_short v[34:35], v42, off
	v_cvt_pk_bf16_f32 v42, v91, s0
	v_lshl_add_u64 v[34:35], v[0:1], 1, s[8:9]
	v_add_u32_e32 v0, v41, v67
	global_store_short v[34:35], v42, off
	v_cvt_pk_bf16_f32 v42, v92, s0
	v_lshl_add_u64 v[34:35], v[0:1], 1, s[8:9]
	v_add_u32_e32 v0, v69, v36
	global_store_short v[34:35], v42, off
	v_cvt_pk_bf16_f32 v42, v86, s0
	v_lshl_add_u64 v[34:35], v[0:1], 1, s[8:9]
	v_add_u32_e32 v0, v37, v69
	global_store_short v[34:35], v42, off
	v_cvt_pk_bf16_f32 v36, v87, s0
	v_lshl_add_u64 v[34:35], v[0:1], 1, s[8:9]
	v_add_u32_e32 v0, v39, v69
	global_store_short v[34:35], v36, off
	v_cvt_pk_bf16_f32 v36, v88, s0
	v_lshl_add_u64 v[34:35], v[0:1], 1, s[8:9]
	v_add_u32_e32 v0, v41, v69
	global_store_short v[34:35], v36, off
	v_cvt_pk_bf16_f32 v36, v89, s0
	v_lshl_add_u64 v[34:35], v[0:1], 1, s[8:9]
	global_store_short v[34:35], v36, off
	v_add_u32_e32 v36, 0xa0, v70
	v_lshlrev_b32_e32 v37, 10, v36
	v_or_b32_e32 v39, 0x400, v37
	v_add_u32_e32 v0, v37, v67
	v_or_b32_e32 v41, 0x800, v37
	v_lshl_add_u64 v[34:35], v[0:1], 1, s[8:9]
	v_add_u32_e32 v0, v39, v67
	v_or_b32_e32 v42, 0xc00, v37
	global_store_short v[34:35], v43, off
	v_cvt_pk_bf16_f32 v43, v82, s0
	v_lshl_add_u64 v[34:35], v[0:1], 1, s[8:9]
	v_add_u32_e32 v0, v41, v67
	global_store_short v[34:35], v43, off
	v_cvt_pk_bf16_f32 v43, v83, s0
	v_lshl_add_u64 v[34:35], v[0:1], 1, s[8:9]
	v_add_u32_e32 v0, v42, v67
	global_store_short v[34:35], v43, off
	v_cvt_pk_bf16_f32 v43, v84, s0
	v_lshl_add_u64 v[34:35], v[0:1], 1, s[8:9]
	v_add_u32_e32 v0, v69, v37
	global_store_short v[34:35], v43, off
	v_cvt_pk_bf16_f32 v43, v78, s0
	v_lshl_add_u64 v[34:35], v[0:1], 1, s[8:9]
	v_add_u32_e32 v0, v39, v69
	global_store_short v[34:35], v43, off
	v_cvt_pk_bf16_f32 v37, v79, s0
	v_lshl_add_u64 v[34:35], v[0:1], 1, s[8:9]
	v_add_u32_e32 v0, v41, v69
	global_store_short v[34:35], v37, off
	v_cvt_pk_bf16_f32 v37, v80, s0
	v_lshl_add_u64 v[34:35], v[0:1], 1, s[8:9]
	v_add_u32_e32 v0, v42, v69
	global_store_short v[34:35], v37, off
	v_cvt_pk_bf16_f32 v37, v81, s0
	v_lshl_add_u64 v[34:35], v[0:1], 1, s[8:9]
	global_store_short v[34:35], v37, off
	v_add_u32_e32 v34, 0xb0, v70
	v_lshlrev_b32_e32 v35, 10, v34
	v_or_b32_e32 v37, 0x400, v35
	v_add_u32_e32 v0, v35, v67
	v_or_b32_e32 v39, 0x800, v35
	v_lshl_add_u64 v[42:43], v[0:1], 1, s[8:9]
	v_add_u32_e32 v0, v37, v67
	v_or_b32_e32 v41, 0xc00, v35
	global_store_short v[42:43], v44, off
	v_cvt_pk_bf16_f32 v44, v142, s0
	v_lshl_add_u64 v[42:43], v[0:1], 1, s[8:9]
	v_add_u32_e32 v0, v39, v67
	global_store_short v[42:43], v44, off
	v_cvt_pk_bf16_f32 v44, v130, s0
	v_lshl_add_u64 v[42:43], v[0:1], 1, s[8:9]
	v_add_u32_e32 v0, v41, v67
	global_store_short v[42:43], v44, off
	v_cvt_pk_bf16_f32 v44, v76, s0
	v_lshl_add_u64 v[42:43], v[0:1], 1, s[8:9]
	v_add_u32_e32 v0, v69, v35
	global_store_short v[42:43], v44, off
	v_cvt_pk_bf16_f32 v44, v74, s0
	v_lshl_add_u64 v[42:43], v[0:1], 1, s[8:9]
	v_add_u32_e32 v0, v37, v69
	global_store_short v[42:43], v44, off
	v_cvt_pk_bf16_f32 v35, v71, s0
	v_lshl_add_u64 v[42:43], v[0:1], 1, s[8:9]
	v_add_u32_e32 v0, v39, v69
	global_store_short v[42:43], v35, off
	v_cvt_pk_bf16_f32 v35, v75, s0
	v_lshl_add_u64 v[42:43], v[0:1], 1, s[8:9]
	v_add_u32_e32 v0, v41, v69
	global_store_short v[42:43], v35, off
	v_cvt_pk_bf16_f32 v35, v73, s0
	v_lshl_add_u64 v[42:43], v[0:1], 1, s[8:9]
	global_store_short v[42:43], v35, off
	v_sub_u32_e32 v35, 0, v40
	v_max_i32_e32 v35, v40, v35
	v_mul_hi_u32 v37, v35, v132
	v_mul_lo_u32 v39, v37, s24
	v_sub_u32_e32 v35, v35, v39
	v_cmp_le_u32_e32 vcc, s24, v35
	v_add_u32_e32 v39, 1, v37
	v_cvt_pk_bf16_f32 v0, v30, s0
	v_cndmask_b32_e32 v37, v37, v39, vcc
	v_subrev_u32_e32 v39, s24, v35
	v_cndmask_b32_e32 v35, v35, v39, vcc
	v_ashrrev_i32_e32 v30, 31, v40
	v_cmp_le_u32_e32 vcc, s24, v35
	v_add_u32_e32 v35, 1, v37
	v_xor_b32_e32 v30, s27, v30
	v_cndmask_b32_e32 v35, v37, v35, vcc
	v_xor_b32_e32 v35, v35, v30
	v_sub_u32_e32 v35, v35, v30
	v_cvt_pk_bf16_f32 v30, v31, s0
	v_lshlrev_b32_e32 v30, 16, v30
	v_cvt_pk_bf16_f32 v31, v33, s0
	v_or_b32_sdwa v30, v30, v0 dst_sel:DWORD dst_unused:UNUSED_PAD src0_sel:DWORD src1_sel:WORD_0
	v_cvt_pk_bf16_f32 v0, v32, s0
	v_lshlrev_b32_e32 v31, 16, v31
	v_or_b32_sdwa v31, v31, v0 dst_sel:DWORD dst_unused:UNUSED_PAD src0_sel:DWORD src1_sel:WORD_0
	v_mul_lo_u32 v0, v35, s88
	v_add_u32_e32 v32, v0, v67
	v_add_u32_e32 v0, v0, v69
	v_mad_u64_u32 v[32:33], s[6:7], v32, s5, v[40:41]
	v_mad_u64_u32 v[28:29], s[6:7], v0, s5, v[40:41]
	v_and_b32_e32 v33, 0x78, v67
	v_lshlrev_b32_e32 v33, 4, v33
	v_xor_b32_e32 v32, v32, v33
	v_mov_b32_e32 v33, v1
	v_and_b32_e32 v29, 0x78, v69
	v_lshlrev_b32_e32 v29, 4, v29
	v_xor_b32_e32 v28, v28, v29
	v_mov_b32_e32 v29, v1
	v_lshl_add_u64 v[32:33], v[32:33], 1, s[10:11]
	v_lshl_add_u64 v[28:29], v[28:29], 1, s[10:11]
	global_store_dwordx2 v[32:33], v[30:31], off
	global_store_dwordx2 v[28:29], v[26:27], off
	v_sub_u32_e32 v26, 0, v38
	v_max_i32_e32 v26, v38, v26
	v_mul_hi_u32 v27, v26, v132
	v_mul_lo_u32 v28, v27, s24
	v_sub_u32_e32 v26, v26, v28
	v_cmp_le_u32_e32 vcc, s24, v26
	v_add_u32_e32 v28, 1, v27
	v_cvt_pk_bf16_f32 v0, v22, s0
	v_cndmask_b32_e32 v27, v27, v28, vcc
	v_subrev_u32_e32 v28, s24, v26
	v_cndmask_b32_e32 v26, v26, v28, vcc
	v_ashrrev_i32_e32 v22, 31, v38
	v_cmp_le_u32_e32 vcc, s24, v26
	v_add_u32_e32 v26, 1, v27
	v_xor_b32_e32 v22, s27, v22
	v_cndmask_b32_e32 v26, v27, v26, vcc
	v_xor_b32_e32 v26, v26, v22
	v_sub_u32_e32 v26, v26, v22
	v_cvt_pk_bf16_f32 v22, v23, s0
	v_lshlrev_b32_e32 v22, 16, v22
	v_cvt_pk_bf16_f32 v23, v25, s0
	v_or_b32_sdwa v22, v22, v0 dst_sel:DWORD dst_unused:UNUSED_PAD src0_sel:DWORD src1_sel:WORD_0
	v_cvt_pk_bf16_f32 v0, v24, s0
	v_lshlrev_b32_e32 v23, 16, v23
	v_or_b32_sdwa v23, v23, v0 dst_sel:DWORD dst_unused:UNUSED_PAD src0_sel:DWORD src1_sel:WORD_0
	v_mul_lo_u32 v0, v26, s88
	v_add_u32_e32 v24, v0, v67
	v_add_u32_e32 v0, v0, v69
	v_mad_u64_u32 v[24:25], s[6:7], v24, s5, v[38:39]
	v_mad_u64_u32 v[20:21], s[6:7], v0, s5, v[38:39]
	v_and_b32_e32 v25, 0x78, v67
	v_lshlrev_b32_e32 v25, 4, v25
	v_xor_b32_e32 v24, v24, v25
	v_mov_b32_e32 v25, v1
	v_and_b32_e32 v21, 0x78, v69
	v_lshlrev_b32_e32 v21, 4, v21
	v_xor_b32_e32 v20, v20, v21
	v_mov_b32_e32 v21, v1
	v_lshl_add_u64 v[24:25], v[24:25], 1, s[10:11]
	v_lshl_add_u64 v[20:21], v[20:21], 1, s[10:11]
	global_store_dwordx2 v[24:25], v[22:23], off
	global_store_dwordx2 v[20:21], v[18:19], off
	v_sub_u32_e32 v18, 0, v36
	v_max_i32_e32 v18, v36, v18
	v_mul_hi_u32 v19, v18, v132
	v_mul_lo_u32 v20, v19, s24
	v_sub_u32_e32 v18, v18, v20
	v_cmp_le_u32_e32 vcc, s24, v18
	v_add_u32_e32 v20, 1, v19
	v_cvt_pk_bf16_f32 v0, v14, s0
	v_cndmask_b32_e32 v19, v19, v20, vcc
	v_subrev_u32_e32 v20, s24, v18
	v_cndmask_b32_e32 v18, v18, v20, vcc
	v_ashrrev_i32_e32 v14, 31, v36
	v_cmp_le_u32_e32 vcc, s24, v18
	v_add_u32_e32 v18, 1, v19
	v_xor_b32_e32 v14, s27, v14
	v_cndmask_b32_e32 v18, v19, v18, vcc
	v_xor_b32_e32 v18, v18, v14
	v_sub_u32_e32 v18, v18, v14
	v_cvt_pk_bf16_f32 v14, v15, s0
	v_lshlrev_b32_e32 v14, 16, v14
	v_cvt_pk_bf16_f32 v15, v17, s0
	v_or_b32_sdwa v14, v14, v0 dst_sel:DWORD dst_unused:UNUSED_PAD src0_sel:DWORD src1_sel:WORD_0
	v_cvt_pk_bf16_f32 v0, v16, s0
	v_lshlrev_b32_e32 v15, 16, v15
	v_or_b32_sdwa v15, v15, v0 dst_sel:DWORD dst_unused:UNUSED_PAD src0_sel:DWORD src1_sel:WORD_0
	v_mul_lo_u32 v0, v18, s88
	v_add_u32_e32 v16, v0, v67
	v_add_u32_e32 v0, v0, v69
	v_mad_u64_u32 v[16:17], s[6:7], v16, s5, v[36:37]
	v_mad_u64_u32 v[12:13], s[6:7], v0, s5, v[36:37]
	v_and_b32_e32 v17, 0x78, v67
	v_lshlrev_b32_e32 v17, 4, v17
	v_xor_b32_e32 v16, v16, v17
	v_mov_b32_e32 v17, v1
	v_and_b32_e32 v13, 0x78, v69
	v_lshlrev_b32_e32 v13, 4, v13
	v_xor_b32_e32 v12, v12, v13
	v_mov_b32_e32 v13, v1
	v_lshl_add_u64 v[16:17], v[16:17], 1, s[10:11]
	v_lshl_add_u64 v[12:13], v[12:13], 1, s[10:11]
	global_store_dwordx2 v[16:17], v[14:15], off
	global_store_dwordx2 v[12:13], v[10:11], off
	v_sub_u32_e32 v10, 0, v34
	v_max_i32_e32 v10, v34, v10
	v_mul_hi_u32 v11, v10, v132
	v_mul_lo_u32 v12, v11, s24
	v_sub_u32_e32 v10, v10, v12
	v_cmp_le_u32_e32 vcc, s24, v10
	v_add_u32_e32 v12, 1, v11
	v_cvt_pk_bf16_f32 v0, v6, s0
	v_cndmask_b32_e32 v11, v11, v12, vcc
	v_subrev_u32_e32 v12, s24, v10
	v_cndmask_b32_e32 v10, v10, v12, vcc
	v_ashrrev_i32_e32 v6, 31, v34
	v_cmp_le_u32_e32 vcc, s24, v10
	v_add_u32_e32 v10, 1, v11
	v_xor_b32_e32 v6, s27, v6
	v_cndmask_b32_e32 v10, v11, v10, vcc
	v_xor_b32_e32 v10, v10, v6
	v_sub_u32_e32 v10, v10, v6
	v_cvt_pk_bf16_f32 v6, v7, s0
	v_lshlrev_b32_e32 v6, 16, v6
	v_cvt_pk_bf16_f32 v7, v9, s0
	v_or_b32_sdwa v6, v6, v0 dst_sel:DWORD dst_unused:UNUSED_PAD src0_sel:DWORD src1_sel:WORD_0
	v_cvt_pk_bf16_f32 v0, v8, s0
	v_lshlrev_b32_e32 v7, 16, v7
	v_or_b32_sdwa v7, v7, v0 dst_sel:DWORD dst_unused:UNUSED_PAD src0_sel:DWORD src1_sel:WORD_0
	v_mul_lo_u32 v0, v10, s88
	v_add_u32_e32 v8, v0, v67
	v_add_u32_e32 v0, v0, v69
	v_mad_u64_u32 v[8:9], s[6:7], v8, s5, v[34:35]
	v_mad_u64_u32 v[4:5], s[6:7], v0, s5, v[34:35]
	v_and_b32_e32 v9, 0x78, v67
	v_lshlrev_b32_e32 v9, 4, v9
	v_xor_b32_e32 v8, v8, v9
	v_mov_b32_e32 v9, v1
	v_and_b32_e32 v5, 0x78, v69
	v_lshlrev_b32_e32 v5, 4, v5
	v_xor_b32_e32 v4, v4, v5
	v_mov_b32_e32 v5, v1
	v_lshl_add_u64 v[8:9], v[8:9], 1, s[10:11]
	v_lshl_add_u64 v[4:5], v[4:5], 1, s[10:11]
	global_store_dwordx2 v[8:9], v[6:7], off
	global_store_dwordx2 v[4:5], v[2:3], off

.LBB0_1242:
	s_getreg_b32 s3, hwreg(HW_REG_HW_ID)
	s_and_b32 s3, s3, 63
	s_lshl_b32 s3, s3, 2
	s_or_b32 s3, s3, 0x27e00
	v_mov_b32_e32 v0, s3
	ds_read_b32 v0, v0
	v_mbcnt_lo_u32_b32 v225, -1, 0
	v_mbcnt_hi_u32_b32 v225, -1, v225
	s_load_dwordx2 s[14:15], s[10:11], 0x1d0
	s_abs_i32 s16, s2
	v_and_b32_e32 v222, 31, v225
	s_waitcnt lgkmcnt(0)
	v_readfirstlane_b32 s3, v0
	v_bfe_u32 v221, v225, 5, 1
	s_lshl_b32 s5, s14, 3
	s_abs_i32 s4, s5
	v_cvt_f32_u32_e32 v0, s4
	s_sub_i32 s17, 0, s4
	v_lshl_add_u32 v226, s3, 6, v225
	s_add_i32 s3, s15, 0xff
	v_rcp_iflag_f32_e32 v0, v0
	s_ashr_i32 s14, s3, 31
	s_lshr_b32 s14, s14, 24
	s_add_i32 s3, s3, s14
	v_mul_f32_e32 v0, 0x4f7ffffe, v0
	v_cvt_u32_f32_e32 v0, v0
	s_xor_b32 s14, s2, s5
	s_ashr_i32 s3, s3, 8
	s_ashr_i32 s14, s14, 31
	v_readfirstlane_b32 s18, v0
	s_mul_i32 s17, s17, s18
	s_mul_hi_u32 s17, s18, s17
	s_add_i32 s18, s18, s17
	s_mul_hi_u32 s17, s16, s18
	s_mul_i32 s18, s17, s4
	s_sub_i32 s16, s16, s18
	s_add_i32 s18, s17, 1
	s_sub_i32 s19, s16, s4
	s_cmp_ge_u32 s16, s4
	s_cselect_b32 s17, s18, s17
	s_cselect_b32 s16, s19, s16
	s_add_i32 s18, s17, 1
	s_cmp_ge_u32 s16, s4
	s_cselect_b32 s4, s18, s17
	s_xor_b32 s4, s4, s14
	s_sub_i32 s4, s4, s14
	s_not_b32 s14, s4
	v_ashrrev_i32_e32 v0, 1, v226
	s_add_i32 s14, s3, s14
	s_mul_i32 s5, s4, s5
	v_and_b32_e32 v0, 0xffffffe0, v0
	s_sub_i32 s5, s2, s5
	s_bfe_u32 s101, s5, 0x30003
	s_xor_b32 s5, s5, s101
	v_lshl_add_u32 v223, s14, 8, v0
	s_ashr_i32 s26, s5, 3
	v_ashrrev_i32_e32 v75, 31, v223
	v_or_b32_e32 v74, v223, v222
	v_mov_b32_e32 v0, s15
	v_mov_b32_e32 v112, 0
	s_and_b32 s2, s5, 7
	v_cmp_gt_i32_e64 s[16:17], s15, v223
	v_mad_i64_i32 v[182:183], s[18:19], s26, v0, v[74:75]
	v_lshlrev_b32_e32 v224, 3, v221
	v_lshlrev_b32_e32 v102, 4, v221
	v_mov_b32_e32 v113, v112
	v_mov_b32_e32 v114, v112
	v_mov_b32_e32 v115, v112
	v_mov_b32_e32 v116, v112
	v_mov_b32_e32 v117, v112
	v_mov_b32_e32 v118, v112
	v_mov_b32_e32 v119, v112
	v_mov_b32_e32 v120, v112
	v_mov_b32_e32 v121, v112
	v_mov_b32_e32 v122, v112
	v_mov_b32_e32 v123, v112
	v_mov_b32_e32 v124, v112
	v_mov_b32_e32 v125, v112
	v_mov_b32_e32 v126, v112
	v_mov_b32_e32 v127, v112
	v_mov_b32_e32 v128, v112
	v_mov_b32_e32 v129, v112
	v_mov_b32_e32 v130, v112
	v_mov_b32_e32 v131, v112
	v_mov_b32_e32 v132, v112
	v_mov_b32_e32 v133, v112
	v_mov_b32_e32 v134, v112
	v_mov_b32_e32 v135, v112
	v_mov_b32_e32 v136, v112
	v_mov_b32_e32 v137, v112
	v_mov_b32_e32 v138, v112
	v_mov_b32_e32 v139, v112
	v_mov_b32_e32 v140, v112
	v_mov_b32_e32 v141, v112
	v_mov_b32_e32 v142, v112
	v_mov_b32_e32 v143, v112
	v_mov_b32_e32 v144, v112
	v_mov_b32_e32 v145, v112
	v_mov_b32_e32 v146, v112
	v_mov_b32_e32 v147, v112
	v_mov_b32_e32 v152, v112
	v_mov_b32_e32 v153, v112
	v_mov_b32_e32 v154, v112
	v_mov_b32_e32 v155, v112
	v_mov_b32_e32 v148, v112
	v_mov_b32_e32 v149, v112
	v_mov_b32_e32 v150, v112
	v_mov_b32_e32 v151, v112
	v_mov_b32_e32 v156, v112
	v_mov_b32_e32 v157, v112
	v_mov_b32_e32 v158, v112
	v_mov_b32_e32 v159, v112
	s_and_saveexec_b64 s[18:19], s[16:17]
	s_cbranch_execz .LBB0_1244
	s_load_dwordx2 s[20:21], s[10:11], 0x208
	s_movk_i32 s22, 0xc00
	s_mul_i32 s82, s2, 0x180
	v_mov_b32_e32 v103, v1
	v_xor_b32_e32 v75, 32, v218
	s_waitcnt lgkmcnt(0)
	v_mov_b64_e32 v[2:3], s[20:21]
	v_mad_u64_u32 v[2:3], s[20:21], v182, s22, v[2:3]
	v_mov_b32_e32 v0, v3
	v_mad_u64_u32 v[4:5], s[20:21], v183, s22, v[0:1]
	v_mov_b32_e32 v3, v4
	v_lshl_add_u64 v[2:3], v[2:3], 0, s[82:83]
	v_lshl_add_u64 v[88:89], v[2:3], 0, v[102:103]
	v_and_b32_e32 v2, 64, v218
	v_lshlrev_b32_e32 v0, 5, v221
	v_add_u32_e32 v90, 64, v2
	global_load_dwordx4 v[58:61], v[88:89], off offset:224
	global_load_dwordx4 v[46:49], v[88:89], off offset:256
	global_load_dwordx4 v[54:57], v[88:89], off offset:288
	global_load_dwordx4 v[42:45], v[88:89], off offset:320
	global_load_dwordx4 v[50:53], v[88:89], off offset:352
	global_load_dwordx4 v[62:65], v[88:89], off offset:192
	global_load_dwordx4 v[66:69], v[88:89], off offset:160
	global_load_dwordx4 v[70:73], v[88:89], off offset:128
	global_load_dwordx4 v[76:79], v[88:89], off offset:96
	global_load_dwordx4 v[80:83], v[88:89], off offset:64
	s_load_dword s20, s[10:11], 0x1e4
	global_load_dwordx4 v[2:5], v0, s[40:41] offset:464
	global_load_dwordx4 v[6:9], v0, s[40:41] offset:448
	global_load_dwordx4 v[10:13], v0, s[40:41] offset:400
	global_load_dwordx4 v[14:17], v0, s[40:41] offset:384
	global_load_dwordx4 v[84:87], v[88:89], off offset:32
	global_load_dwordx4 v[18:21], v0, s[40:41] offset:336
	global_load_dwordx4 v[22:25], v0, s[40:41] offset:320
	global_load_dwordx4 v[26:29], v0, s[40:41] offset:272
	global_load_dwordx4 v[30:33], v0, s[40:41] offset:256
	global_load_dwordx4 v[34:37], v0, s[40:41] offset:208
	global_load_dwordx4 v[38:41], v0, s[40:41] offset:192
	v_cmp_lt_i32_e32 vcc, v75, v90
	global_load_dwordx4 v[88:91], v[88:89], off
	s_mov_b32 s21, s74
	v_cndmask_b32_e32 v75, v218, v75, vcc
	v_lshlrev_b32_e32 v103, 2, v75
	s_waitcnt vmcnt(0)
	v_and_b32_e32 v145, 0xffff0000, v61
	v_lshlrev_b32_e32 v144, 16, v61
	v_and_b32_e32 v141, 0xffff0000, v58
	v_lshlrev_b32_e32 v140, 16, v58
	v_and_b32_e32 v147, 0xffff0000, v59
	v_and_b32_e32 v117, 0xffff0000, v84
	v_lshlrev_b32_e32 v116, 16, v84
	v_and_b32_e32 v171, 0xffff0000, v85
	v_lshlrev_b32_e32 v170, 16, v85
	v_and_b32_e32 v119, 0xffff0000, v86
	v_lshlrev_b32_e32 v118, 16, v86
	v_and_b32_e32 v169, 0xffff0000, v87
	v_lshlrev_b32_e32 v168, 16, v87
	v_and_b32_e32 v185, 0xffff0000, v88
	v_lshlrev_b32_e32 v184, 16, v88
	v_mul_f32_e32 v84, v185, v185
	v_pk_fma_f32 v[84:85], v[184:185], v[184:185], v[84:85] op_sel_hi:[1,1,0]
	v_and_b32_e32 v203, 0xffff0000, v89
	v_lshlrev_b32_e32 v202, 16, v89
	v_pk_fma_f32 v[84:85], v[202:203], v[202:203], v[84:85]
	v_mul_f32_e32 v86, v203, v203
	v_pk_add_f32 v[84:85], v[86:87], v[84:85] op_sel_hi:[0,1]
	v_and_b32_e32 v199, 0xffff0000, v90
	v_lshlrev_b32_e32 v198, 16, v90
	v_pk_fma_f32 v[84:85], v[198:199], v[198:199], v[84:85]
	v_mul_f32_e32 v86, v199, v199
	v_pk_add_f32 v[84:85], v[86:87], v[84:85] op_sel_hi:[0,1]
	v_and_b32_e32 v201, 0xffff0000, v91
	v_lshlrev_b32_e32 v200, 16, v91
	v_pk_fma_f32 v[84:85], v[200:201], v[200:201], v[84:85]
	v_mul_f32_e32 v86, v201, v201
	v_pk_add_f32 v[84:85], v[86:87], v[84:85] op_sel_hi:[0,1]
	v_pk_fma_f32 v[84:85], v[116:117], v[116:117], v[84:85]
	v_mul_f32_e32 v86, v117, v117
	v_pk_add_f32 v[84:85], v[86:87], v[84:85] op_sel_hi:[0,1]
	v_pk_fma_f32 v[84:85], v[170:171], v[170:171], v[84:85]
	v_mul_f32_e32 v86, v171, v171
	v_pk_add_f32 v[84:85], v[86:87], v[84:85] op_sel_hi:[0,1]
	v_pk_fma_f32 v[84:85], v[118:119], v[118:119], v[84:85]
	v_mul_f32_e32 v86, v119, v119
	v_pk_add_f32 v[84:85], v[86:87], v[84:85] op_sel_hi:[0,1]
	v_pk_fma_f32 v[84:85], v[168:169], v[168:169], v[84:85]
	v_mul_f32_e32 v86, v169, v169
	v_and_b32_e32 v121, 0xffff0000, v80
	v_lshlrev_b32_e32 v120, 16, v80
	v_pk_add_f32 v[84:85], v[86:87], v[84:85] op_sel_hi:[0,1]
	v_pk_fma_f32 v[84:85], v[120:121], v[120:121], v[84:85]
	v_mul_f32_e32 v86, v121, v121
	v_and_b32_e32 v123, 0xffff0000, v81
	v_lshlrev_b32_e32 v122, 16, v81
	v_pk_add_f32 v[84:85], v[86:87], v[84:85] op_sel_hi:[0,1]
	v_lshlrev_b32_e32 v146, 16, v59
	v_and_b32_e32 v143, 0xffff0000, v60
	v_lshlrev_b32_e32 v142, 16, v60
	v_and_b32_e32 v137, 0xffff0000, v62
	v_lshlrev_b32_e32 v136, 16, v62
	v_and_b32_e32 v151, 0xffff0000, v63
	v_lshlrev_b32_e32 v150, 16, v63
	v_and_b32_e32 v139, 0xffff0000, v64
	v_lshlrev_b32_e32 v138, 16, v64
	v_and_b32_e32 v149, 0xffff0000, v65
	v_lshlrev_b32_e32 v148, 16, v65
	v_and_b32_e32 v133, 0xffff0000, v66
	v_lshlrev_b32_e32 v132, 16, v66
	v_and_b32_e32 v155, 0xffff0000, v67
	v_lshlrev_b32_e32 v154, 16, v67
	v_and_b32_e32 v135, 0xffff0000, v68
	v_lshlrev_b32_e32 v134, 16, v68
	v_and_b32_e32 v153, 0xffff0000, v69
	v_lshlrev_b32_e32 v152, 16, v69
	v_and_b32_e32 v129, 0xffff0000, v70
	v_lshlrev_b32_e32 v128, 16, v70
	v_and_b32_e32 v159, 0xffff0000, v71
	v_lshlrev_b32_e32 v158, 16, v71
	v_and_b32_e32 v131, 0xffff0000, v72
	v_lshlrev_b32_e32 v130, 16, v72
	v_and_b32_e32 v157, 0xffff0000, v73
	v_lshlrev_b32_e32 v156, 16, v73
	global_load_dwordx4 v[58:61], v0, s[40:41] offset:80
	global_load_dwordx4 v[66:69], v0, s[40:41] offset:64
	global_load_dwordx4 v[70:73], v0, s[40:41] offset:16
	global_load_dwordx4 v[62:65], v0, s[42:43] offset:16
	v_pk_fma_f32 v[84:85], v[122:123], v[122:123], v[84:85]
	v_mul_f32_e32 v86, v123, v123
	v_and_b32_e32 v165, 0xffff0000, v82
	v_lshlrev_b32_e32 v164, 16, v82
	v_pk_add_f32 v[84:85], v[86:87], v[84:85] op_sel_hi:[0,1]
	v_lshlrev_b32_e32 v166, 16, v83
	v_pk_fma_f32 v[84:85], v[164:165], v[164:165], v[84:85]
	v_mul_f32_e32 v86, v165, v165
	v_and_b32_e32 v167, 0xffff0000, v83
	v_mov_b32_e32 v80, v166
	v_mov_b32_e32 v81, v165
	v_pk_add_f32 v[84:85], v[86:87], v[84:85] op_sel_hi:[0,1]
	v_lshlrev_b32_e32 v124, 16, v76
	v_pk_fma_f32 v[80:81], v[80:81], v[80:81], v[84:85]
	v_mul_f32_e32 v84, v167, v167
	v_and_b32_e32 v125, 0xffff0000, v76
	v_mov_b32_e32 v82, v124
	v_mov_b32_e32 v83, v167
	v_pk_add_f32 v[80:81], v[84:85], v[80:81] op_sel_hi:[0,1]
	v_lshlrev_b32_e32 v126, 16, v77
	v_pk_fma_f32 v[80:81], v[82:83], v[82:83], v[80:81]
	v_mul_f32_e32 v82, v125, v125
	v_and_b32_e32 v127, 0xffff0000, v77
	v_mov_b32_e32 v76, v126
	v_mov_b32_e32 v77, v125
	v_pk_add_f32 v[80:81], v[82:83], v[80:81] op_sel_hi:[0,1]
	v_lshlrev_b32_e32 v160, 16, v78
	v_pk_fma_f32 v[76:77], v[76:77], v[76:77], v[80:81]
	v_mul_f32_e32 v80, v127, v127
	v_and_b32_e32 v161, 0xffff0000, v78
	v_mov_b32_e32 v92, v160
	v_mov_b32_e32 v93, v127
	v_pk_add_f32 v[76:77], v[80:81], v[76:77] op_sel_hi:[0,1]
	v_lshlrev_b32_e32 v162, 16, v79
	v_pk_fma_f32 v[76:77], v[92:93], v[92:93], v[76:77]
	v_mul_f32_e32 v80, v161, v161
	v_and_b32_e32 v163, 0xffff0000, v79
	v_mov_b32_e32 v78, v162
	v_mov_b32_e32 v79, v161
	v_pk_add_f32 v[76:77], v[80:81], v[76:77] op_sel_hi:[0,1]
	v_pk_fma_f32 v[76:77], v[78:79], v[78:79], v[76:77]
	v_mul_f32_e32 v78, v163, v163
	v_pk_add_f32 v[76:77], v[78:79], v[76:77] op_sel_hi:[0,1]
	s_waitcnt lgkmcnt(0)
	v_add_lshl_u32 v78, v74, s20, 5
	v_or_b32_e32 v74, v78, v224
	v_mov_b32_e32 v94, v128
	v_mov_b32_e32 v95, v163
	v_ashrrev_i32_e32 v75, 31, v74
	v_pk_fma_f32 v[216:217], v[94:95], v[94:95], v[76:77]
	v_lshlrev_b64 v[76:77], 2, v[74:75]
	v_ashrrev_i32_e32 v75, 31, v78
	v_lshlrev_b64 v[74:75], 2, v[74:75]
	v_lshl_add_u64 v[204:205], s[56:57], 0, v[76:77]
	v_lshl_add_u64 v[206:207], s[58:59], 0, v[76:77]
	v_lshl_add_u64 v[214:215], s[56:57], 0, v[74:75]
	v_lshl_add_u64 v[208:209], s[58:59], 0, v[74:75]
	global_load_dwordx4 v[98:101], v0, s[40:41]
	global_load_dwordx4 v[82:85], v0, s[42:43]
	global_load_dwordx4 v[90:93], v0, s[40:41] offset:144
	global_load_dwordx4 v[74:77], v0, s[42:43] offset:144
	global_load_dwordx4 v[94:97], v0, s[40:41] offset:128
	global_load_dwordx4 v[86:89], v0, s[42:43] offset:128
	global_load_dwordx2 v[186:187], v[214:215], off offset:24
	global_load_dwordx4 v[78:81], v[214:215], off offset:8
	global_load_dwordx2 v[188:189], v[208:209], off offset:24
	v_lshlrev_b32_e32 v104, 16, v57
	v_and_b32_e32 v176, 0xffff0000, v57
	v_and_b32_e32 v195, 0xffff0000, v54
	v_lshlrev_b32_e32 v194, 16, v54
	v_and_b32_e32 v197, 0xffff0000, v50
	v_lshlrev_b32_e32 v196, 16, v50
	v_and_b32_e32 v193, 0xffff0000, v55
	v_lshlrev_b32_e32 v192, 16, v55
	v_and_b32_e32 v55, 0xffff0000, v51
	v_lshlrev_b32_e32 v54, 16, v51
	v_and_b32_e32 v51, 0xffff0000, v56
	v_lshlrev_b32_e32 v50, 16, v56
	v_lshlrev_b32_e32 v56, 16, v46
	v_and_b32_e32 v57, 0xffff0000, v46
	v_pk_mul_f32 v[234:235], v[56:57], v[56:57]
	v_lshlrev_b32_e32 v210, 16, v47
	v_pk_mov_b32 v[216:217], v[234:235], v[216:217] op_sel:[1,0]
	v_mov_b32_e32 v234, v56
	v_mov_b32_e32 v235, v129
	v_and_b32_e32 v211, 0xffff0000, v47
	v_pk_fma_f32 v[216:217], v[234:235], v[234:235], v[216:217]
	v_mov_b32_e32 v234, v210
	v_mov_b32_e32 v235, v158
	v_lshlrev_b32_e32 v46, 16, v48
	v_pk_fma_f32 v[216:217], v[234:235], v[234:235], v[216:217]
	v_mov_b32_e32 v234, v211
	v_mov_b32_e32 v235, v159
	v_and_b32_e32 v47, 0xffff0000, v48
	v_pk_fma_f32 v[216:217], v[234:235], v[234:235], v[216:217]
	v_mov_b32_e32 v234, v46
	v_mov_b32_e32 v235, v130
	v_pk_fma_f32 v[216:217], v[234:235], v[234:235], v[216:217]
	v_mov_b32_e32 v234, v47
	v_mov_b32_e32 v235, v131
	v_lshlrev_b32_e32 v108, 16, v49
	v_and_b32_e32 v190, 0xffff0000, v49
	v_mov_b32_e32 v109, v156
	v_pk_fma_f32 v[216:217], v[234:235], v[234:235], v[216:217]
	v_mov_b32_e32 v234, v190
	v_mov_b32_e32 v235, v157
	v_pk_fma_f32 v[216:217], v[108:109], v[108:109], v[216:217]
	v_mov_b32_e32 v105, v152
	v_pk_fma_f32 v[216:217], v[234:235], v[234:235], v[216:217]
	v_mov_b32_e32 v234, v194
	v_mov_b32_e32 v235, v132
	v_pk_fma_f32 v[216:217], v[234:235], v[234:235], v[216:217]
	v_mov_b32_e32 v234, v195
	v_mov_b32_e32 v235, v133
	v_pk_fma_f32 v[216:217], v[234:235], v[234:235], v[216:217]
	v_mov_b32_e32 v234, v192
	v_mov_b32_e32 v235, v154
	v_pk_fma_f32 v[216:217], v[234:235], v[234:235], v[216:217]
	v_mov_b32_e32 v234, v193
	v_mov_b32_e32 v235, v155
	v_pk_fma_f32 v[216:217], v[234:235], v[234:235], v[216:217]
	v_mov_b32_e32 v234, v50
	v_mov_b32_e32 v235, v134
	v_pk_fma_f32 v[216:217], v[234:235], v[234:235], v[216:217]
	v_mov_b32_e32 v234, v51
	v_mov_b32_e32 v235, v135
	v_pk_fma_f32 v[216:217], v[234:235], v[234:235], v[216:217]
	v_lshlrev_b32_e32 v212, 16, v42
	v_mov_b32_e32 v234, v176
	v_mov_b32_e32 v235, v153
	v_pk_fma_f32 v[216:217], v[104:105], v[104:105], v[216:217]
	v_and_b32_e32 v213, 0xffff0000, v42
	v_pk_fma_f32 v[216:217], v[234:235], v[234:235], v[216:217]
	v_mov_b32_e32 v234, v212
	v_mov_b32_e32 v235, v136
	v_lshlrev_b32_e32 v48, 16, v43
	v_pk_fma_f32 v[216:217], v[234:235], v[234:235], v[216:217]
	v_mov_b32_e32 v234, v213
	v_mov_b32_e32 v235, v137
	v_and_b32_e32 v49, 0xffff0000, v43
	v_pk_fma_f32 v[216:217], v[234:235], v[234:235], v[216:217]
	v_mov_b32_e32 v234, v48
	v_mov_b32_e32 v235, v150
	v_and_b32_e32 v191, 0xffff0000, v45
	v_lshlrev_b32_e32 v42, 16, v44
	v_pk_fma_f32 v[216:217], v[234:235], v[234:235], v[216:217]
	v_mov_b32_e32 v234, v49
	v_mov_b32_e32 v235, v151
	v_lshlrev_b32_e32 v111, 16, v45
	v_mov_b32_e32 v110, v191
	v_and_b32_e32 v43, 0xffff0000, v44
	v_pk_fma_f32 v[216:217], v[234:235], v[234:235], v[216:217]
	v_mov_b32_e32 v234, v42
	v_mov_b32_e32 v235, v138
	v_pk_mul_f32 v[178:179], v[148:149], v[148:149]
	v_pk_mul_f32 v[228:229], v[110:111], v[110:111]
	v_pk_fma_f32 v[216:217], v[234:235], v[234:235], v[216:217]
	v_mov_b32_e32 v234, v43
	v_mov_b32_e32 v235, v139
	v_pk_fma_f32 v[216:217], v[234:235], v[234:235], v[216:217]
	v_pk_mov_b32 v[234:235], v[228:229], v[178:179] op_sel:[1,0]
	v_pk_mul_f32 v[174:175], v[140:141], v[140:141]
	v_pk_mul_f32 v[232:233], v[196:197], v[196:197]
	v_pk_add_f32 v[216:217], v[234:235], v[216:217]
	v_mov_b32_e32 v229, v179
	v_pk_add_f32 v[178:179], v[228:229], v[216:217]
	v_mov_b32_e32 v216, v232
	v_mov_b32_e32 v217, v174
	v_pk_mul_f32 v[172:173], v[146:147], v[146:147]
	v_pk_mul_f32 v[44:45], v[54:55], v[54:55]
	v_pk_add_f32 v[178:179], v[216:217], v[178:179]
	v_mov_b32_e32 v174, v233
	v_lshlrev_b32_e32 v107, 16, v53
	v_and_b32_e32 v177, 0xffff0000, v53
	v_and_b32_e32 v53, 0xffff0000, v52
	v_lshlrev_b32_e32 v52, 16, v52
	v_pk_add_f32 v[174:175], v[174:175], v[178:179]
	v_mov_b32_e32 v178, v44
	v_mov_b32_e32 v179, v172
	v_pk_mul_f32 v[114:115], v[142:143], v[142:143]
	v_pk_mul_f32 v[234:235], v[52:53], v[52:53]
	v_pk_add_f32 v[174:175], v[178:179], v[174:175]
	v_mov_b32_e32 v172, v45
	v_mov_b32_e32 v106, v177
	v_pk_add_f32 v[44:45], v[172:173], v[174:175]
	v_mov_b32_e32 v172, v234
	v_mov_b32_e32 v173, v114
	v_pk_mul_f32 v[112:113], v[144:145], v[144:145]
	v_pk_mul_f32 v[230:231], v[106:107], v[106:107]
	v_pk_add_f32 v[44:45], v[172:173], v[44:45]
	v_mov_b32_e32 v114, v235
	v_pk_add_f32 v[44:45], v[114:115], v[44:45]
	v_pk_mov_b32 v[114:115], v[230:231], v[112:113] op_sel:[1,0]
	v_mov_b32_e32 v231, v113
	v_pk_add_f32 v[44:45], v[114:115], v[44:45]
	s_mov_b32 s20, s93
	v_pk_add_f32 v[44:45], v[230:231], v[44:45]
	ds_bpermute_b32 v113, v103, v45
	ds_bpermute_b32 v112, v103, v44
	s_waitcnt vmcnt(9)
	v_mov_b32_e32 v178, v65
	global_load_dwordx4 v[172:175], v[208:209], off offset:8
	global_load_dwordx4 v[228:231], v0, s[42:43] offset:80
	global_load_dwordx4 v[232:235], v0, s[42:43] offset:64
	global_load_dwordx4 v[236:239], v0, s[42:43] offset:192
	s_waitcnt lgkmcnt(0)
	v_pk_add_f32 v[44:45], v[44:45], v[112:113]
	s_waitcnt vmcnt(9)
	v_mov_b32_e32 v179, v77
	v_pk_fma_f32 v[44:45], v[44:45], s[20:21], v[180:181] op_sel_hi:[1,1,0]
	s_waitcnt vmcnt(6)
	v_mov_b32_e32 v240, v187
	v_mul_f32_e32 v65, 0x4b800000, v45
	v_cmp_gt_f32_e32 vcc, s91, v45
	s_waitcnt vmcnt(4)
	v_mov_b32_e32 v241, v189
	v_cndmask_b32_e32 v45, v45, v65, vcc
	v_rsq_f32_e32 v45, v45
	s_nop 0
	v_mul_f32_e32 v65, 0x45800000, v45
	v_cndmask_b32_e32 v45, v45, v65, vcc
	v_mul_f32_e32 v106, 0x3dd53b95, v45
	v_pk_mul_f32 v[112:113], v[106:107], v[184:185] op_sel_hi:[0,1]
	v_pk_mul_f32 v[112:113], v[98:99], v[112:113]
	v_pk_mul_f32 v[98:99], v[106:107], v[202:203] op_sel_hi:[0,1]
	v_pk_mul_f32 v[114:115], v[100:101], v[98:99]
	v_cvt_pk_bf16_f32 v112, v112, v113
	v_cvt_pk_bf16_f32 v113, v114, v115
	v_pk_mul_f32 v[114:115], v[106:107], v[198:199] op_sel_hi:[0,1]
	v_pk_mul_f32 v[116:117], v[106:107], v[116:117] op_sel_hi:[0,1]
	v_pk_mul_f32 v[114:115], v[70:71], v[114:115]
	v_pk_mul_f32 v[70:71], v[106:107], v[200:201] op_sel_hi:[0,1]
	v_pk_mul_f32 v[116:117], v[66:67], v[116:117]
	v_pk_mul_f32 v[66:67], v[106:107], v[170:171] op_sel_hi:[0,1]
	v_pk_mul_f32 v[184:185], v[72:73], v[70:71]
	v_pk_mul_f32 v[170:171], v[68:69], v[66:67]
	global_load_dwordx4 v[98:101], v0, s[42:43] offset:208
	global_load_dwordx4 v[70:73], v[214:215], off offset:80
	global_load_dwordx4 v[198:201], v[214:215], off offset:64
	v_cvt_pk_bf16_f32 v114, v114, v115
	global_load_dwordx4 v[66:69], v[208:209], off offset:80
	global_load_dwordx4 v[214:217], v[208:209], off offset:64
	v_cvt_pk_bf16_f32 v115, v184, v185
	v_cvt_pk_bf16_f32 v116, v116, v117
	v_cvt_pk_bf16_f32 v117, v170, v171
	global_load_dwordx2 v[170:171], v[204:205], off
	global_load_dwordx2 v[184:185], v[206:207], off
	v_pk_mul_f32 v[168:169], v[106:107], v[168:169] op_sel_hi:[0,1]
	v_pk_mul_f32 v[118:119], v[106:107], v[118:119] op_sel_hi:[0,1]
	v_pk_mul_f32 v[60:61], v[60:61], v[168:169]
	v_pk_mul_f32 v[58:59], v[58:59], v[118:119]
	v_cvt_pk_bf16_f32 v119, v60, v61
	v_pk_mul_f32 v[60:61], v[106:107], v[120:121] op_sel_hi:[0,1]
	v_pk_mul_f32 v[60:61], v[94:95], v[60:61]
	v_mul_f32_e32 v0, 0x4b800000, v44
	v_cvt_pk_bf16_f32 v120, v60, v61
	v_pk_mul_f32 v[60:61], v[106:107], v[122:123] op_sel_hi:[0,1]
	v_pk_mul_f32 v[60:61], v[96:97], v[60:61]
	v_cmp_gt_f32_e32 vcc, s91, v44
	v_cvt_pk_bf16_f32 v121, v60, v61
	v_pk_mul_f32 v[60:61], v[106:107], v[164:165] op_sel_hi:[0,1]
	v_pk_mul_f32 v[60:61], v[90:91], v[60:61]
	v_cndmask_b32_e32 v0, v44, v0, vcc
	v_cvt_pk_bf16_f32 v122, v60, v61
	v_pk_mul_f32 v[60:61], v[106:107], v[166:167] op_sel_hi:[0,1]
	v_pk_mul_f32 v[60:61], v[92:93], v[60:61]
	v_rsq_f32_e32 v0, v0
	v_cvt_pk_bf16_f32 v123, v60, v61
	v_pk_mul_f32 v[60:61], v[106:107], v[124:125] op_sel_hi:[0,1]
	v_pk_mul_f32 v[38:39], v[38:39], v[60:61]
	v_cvt_pk_bf16_f32 v118, v58, v59
	v_cvt_pk_bf16_f32 v124, v38, v39
	v_pk_mul_f32 v[38:39], v[106:107], v[126:127] op_sel_hi:[0,1]
	v_pk_mul_f32 v[38:39], v[40:41], v[38:39]
	v_mov_b32_e32 v58, v189
	v_cvt_pk_bf16_f32 v125, v38, v39
	v_pk_mul_f32 v[38:39], v[106:107], v[160:161] op_sel_hi:[0,1]
	v_pk_mul_f32 v[34:35], v[34:35], v[38:39]
	v_mov_b32_e32 v59, v187
	v_cvt_pk_bf16_f32 v126, v34, v35
	v_pk_mul_f32 v[34:35], v[106:107], v[162:163] op_sel_hi:[0,1]
	v_pk_mul_f32 v[34:35], v[36:37], v[34:35]
	s_nop 0
	v_cvt_pk_bf16_f32 v127, v34, v35
	v_pk_mul_f32 v[34:35], v[106:107], v[128:129] op_sel_hi:[0,1]
	v_pk_mul_f32 v[30:31], v[30:31], v[34:35]
	s_nop 0
	v_cvt_pk_bf16_f32 v128, v30, v31
	v_pk_mul_f32 v[30:31], v[106:107], v[158:159] op_sel_hi:[0,1]
	v_pk_mul_f32 v[30:31], v[32:33], v[30:31]
	s_nop 0
	v_cvt_pk_bf16_f32 v129, v30, v31
	v_pk_mul_f32 v[30:31], v[106:107], v[130:131] op_sel_hi:[0,1]
	v_pk_mul_f32 v[26:27], v[26:27], v[30:31]
	s_nop 0
	v_cvt_pk_bf16_f32 v130, v26, v27
	v_pk_mul_f32 v[26:27], v[106:107], v[156:157] op_sel_hi:[0,1]
	v_pk_mul_f32 v[26:27], v[28:29], v[26:27]
	s_nop 0
	v_cvt_pk_bf16_f32 v131, v26, v27
	v_pk_mul_f32 v[26:27], v[106:107], v[132:133] op_sel_hi:[0,1]
	v_pk_mul_f32 v[22:23], v[22:23], v[26:27]
	s_nop 0
	v_cvt_pk_bf16_f32 v132, v22, v23
	v_pk_mul_f32 v[22:23], v[106:107], v[154:155] op_sel_hi:[0,1]
	v_pk_mul_f32 v[22:23], v[24:25], v[22:23]
	s_nop 0
	v_cvt_pk_bf16_f32 v133, v22, v23
	v_pk_mul_f32 v[22:23], v[106:107], v[134:135] op_sel_hi:[0,1]
	v_pk_mul_f32 v[18:19], v[18:19], v[22:23]
	s_nop 0
	v_cvt_pk_bf16_f32 v134, v18, v19
	v_pk_mul_f32 v[18:19], v[106:107], v[152:153] op_sel_hi:[0,1]
	v_pk_mul_f32 v[18:19], v[20:21], v[18:19]
	s_nop 0
	v_cvt_pk_bf16_f32 v135, v18, v19
	v_pk_mul_f32 v[18:19], v[106:107], v[136:137] op_sel_hi:[0,1]
	v_pk_mul_f32 v[14:15], v[14:15], v[18:19]
	s_nop 0
	v_cvt_pk_bf16_f32 v136, v14, v15
	v_pk_mul_f32 v[14:15], v[106:107], v[150:151] op_sel_hi:[0,1]
	v_pk_mul_f32 v[14:15], v[16:17], v[14:15]
	s_nop 0
	v_cvt_pk_bf16_f32 v137, v14, v15
	v_pk_mul_f32 v[14:15], v[106:107], v[138:139] op_sel_hi:[0,1]
	v_pk_mul_f32 v[10:11], v[10:11], v[14:15]
	s_nop 0
	v_cvt_pk_bf16_f32 v138, v10, v11
	v_pk_mul_f32 v[10:11], v[106:107], v[148:149] op_sel_hi:[0,1]
	v_pk_mul_f32 v[10:11], v[12:13], v[10:11]
	s_nop 0
	v_cvt_pk_bf16_f32 v139, v10, v11
	v_pk_mul_f32 v[10:11], v[106:107], v[140:141] op_sel_hi:[0,1]
	v_pk_mul_f32 v[6:7], v[6:7], v[10:11]
	s_nop 0
	v_cvt_pk_bf16_f32 v140, v6, v7
	v_pk_mul_f32 v[6:7], v[106:107], v[146:147] op_sel_hi:[0,1]
	v_pk_mul_f32 v[6:7], v[8:9], v[6:7]
	s_nop 0
	v_cvt_pk_bf16_f32 v141, v6, v7
	v_pk_mul_f32 v[6:7], v[106:107], v[142:143] op_sel_hi:[0,1]
	v_pk_mul_f32 v[2:3], v[2:3], v[6:7]
	s_nop 0
	v_cvt_pk_bf16_f32 v142, v2, v3
	v_pk_mul_f32 v[2:3], v[106:107], v[144:145] op_sel_hi:[0,1]
	v_pk_mul_f32 v[2:3], v[2:3], v[4:5]
	s_nop 0
	v_cvt_pk_bf16_f32 v143, v2, v3
	v_mul_f32_e32 v2, 0x45800000, v0
	v_cndmask_b32_e32 v0, v0, v2, vcc
	v_mul_f32_e32 v0, 0x3dd53b95, v0
	v_pk_mul_f32 v[2:3], v[0:1], v[56:57] op_sel_hi:[0,1]
	v_pk_mul_f32 v[2:3], v[2:3], v[82:83]
	v_pk_mul_f32 v[4:5], v[0:1], v[212:213] op_sel_hi:[0,1]
	v_pk_mul_f32 v[4:5], v[4:5], v[86:87]
	s_waitcnt vmcnt(0)
	v_pk_mul_f32 v[6:7], v[2:3], v[184:185]
	v_pk_mul_f32 v[10:11], v[0:1], v[190:191] op_sel_hi:[0,1]
	v_pk_fma_f32 v[6:7], v[170:171], v[4:5], v[6:7]
	v_pk_mul_f32 v[4:5], v[4:5], v[184:185]
	v_cvt_pk_bf16_f32 v148, v6, v7
	v_pk_fma_f32 v[2:3], v[2:3], v[170:171], v[4:5] neg_lo:[0,0,1] neg_hi:[0,0,1]
	v_pk_mul_f32 v[4:5], v[0:1], v[48:49] op_sel_hi:[0,1]
	v_cvt_pk_bf16_f32 v144, v2, v3
	v_pk_mul_f32 v[2:3], v[0:1], v[210:211] op_sel_hi:[0,1]
	v_pk_mul_f32 v[2:3], v[2:3], v[84:85]
	v_pk_mul_f32 v[4:5], v[4:5], v[88:89]
	v_pk_mul_f32 v[6:7], v[2:3], v[172:173]
	v_pk_mul_f32 v[10:11], v[10:11], v[178:179]
	v_pk_fma_f32 v[6:7], v[78:79], v[4:5], v[6:7]
	v_pk_mul_f32 v[4:5], v[4:5], v[172:173]
	v_cvt_pk_bf16_f32 v149, v6, v7
	v_pk_fma_f32 v[2:3], v[2:3], v[78:79], v[4:5] neg_lo:[0,0,1] neg_hi:[0,0,1]
	v_pk_mul_f32 v[4:5], v[0:1], v[42:43] op_sel_hi:[0,1]
	v_cvt_pk_bf16_f32 v145, v2, v3
	v_pk_mul_f32 v[2:3], v[0:1], v[46:47] op_sel_hi:[0,1]
	v_pk_mul_f32 v[2:3], v[2:3], v[62:63]
	v_pk_mul_f32 v[4:5], v[4:5], v[74:75]
	v_pk_mul_f32 v[6:7], v[2:3], v[174:175]
	v_pk_mul_f32 v[12:13], v[10:11], v[240:241]
	v_pk_fma_f32 v[6:7], v[80:81], v[4:5], v[6:7]
	v_pk_mul_f32 v[4:5], v[4:5], v[174:175]
	v_cvt_pk_bf16_f32 v150, v6, v7
	v_pk_fma_f32 v[2:3], v[2:3], v[80:81], v[4:5] neg_lo:[0,0,1] neg_hi:[0,0,1]
	s_nop 0
	v_cvt_pk_bf16_f32 v146, v2, v3
	v_mul_f32_e32 v2, v0, v108
	v_mul_f32_e32 v3, v2, v64
	v_mul_f32_e32 v2, v0, v111
	v_mul_f32_e32 v5, v2, v76
	v_mul_f32_e32 v2, v3, v186
	v_mul_f32_e32 v4, v5, v188
	v_mul_f32_e32 v6, v186, v5
	v_mul_f32_e32 v8, v3, v188
	v_mov_b32_e32 v3, v12
	v_mov_b32_e32 v5, v13
	v_pk_add_f32 v[2:3], v[2:3], v[4:5] neg_lo:[0,1] neg_hi:[0,1]
	v_pk_mul_f32 v[4:5], v[0:1], v[196:197] op_sel_hi:[0,1]
	v_cvt_pk_bf16_f32 v147, v2, v3
	v_pk_mul_f32 v[2:3], v[58:59], v[10:11]
	v_pk_mul_f32 v[4:5], v[4:5], v[236:237]
	v_mov_b32_e32 v7, v3
	v_mov_b32_e32 v9, v2
	v_pk_add_f32 v[2:3], v[6:7], v[8:9]
	v_pk_mul_f32 v[10:11], v[0:1], v[176:177] op_sel_hi:[0,1]
	v_cvt_pk_bf16_f32 v151, v2, v3
	v_pk_mul_f32 v[2:3], v[0:1], v[194:195] op_sel_hi:[0,1]
	v_pk_mul_f32 v[2:3], v[2:3], v[232:233]
	s_nop 0
	v_pk_mul_f32 v[6:7], v[2:3], v[214:215]
	s_nop 0
	v_pk_fma_f32 v[6:7], v[198:199], v[4:5], v[6:7]
	v_pk_mul_f32 v[4:5], v[4:5], v[214:215]
	v_cvt_pk_bf16_f32 v156, v6, v7
	v_pk_fma_f32 v[2:3], v[2:3], v[198:199], v[4:5] neg_lo:[0,0,1] neg_hi:[0,0,1]
	v_pk_mul_f32 v[4:5], v[0:1], v[54:55] op_sel_hi:[0,1]
	v_cvt_pk_bf16_f32 v152, v2, v3
	v_pk_mul_f32 v[2:3], v[0:1], v[192:193] op_sel_hi:[0,1]
	v_pk_mul_f32 v[2:3], v[2:3], v[234:235]
	v_pk_mul_f32 v[4:5], v[4:5], v[238:239]
	v_pk_mul_f32 v[6:7], v[2:3], v[216:217]
	s_nop 0
	v_pk_fma_f32 v[6:7], v[200:201], v[4:5], v[6:7]
	v_pk_mul_f32 v[4:5], v[4:5], v[216:217]
	v_cvt_pk_bf16_f32 v157, v6, v7
	v_pk_fma_f32 v[2:3], v[2:3], v[200:201], v[4:5] neg_lo:[0,0,1] neg_hi:[0,0,1]
	v_pk_mul_f32 v[4:5], v[0:1], v[52:53] op_sel_hi:[0,1]
	v_cvt_pk_bf16_f32 v153, v2, v3
	v_pk_mul_f32 v[2:3], v[0:1], v[50:51] op_sel_hi:[0,1]
	v_pk_mul_f32 v[2:3], v[2:3], v[228:229]
	v_pk_mul_f32 v[4:5], v[4:5], v[98:99]
	v_pk_mul_f32 v[6:7], v[2:3], v[66:67]
	s_nop 0
	v_pk_fma_f32 v[6:7], v[70:71], v[4:5], v[6:7]
	v_pk_mul_f32 v[4:5], v[4:5], v[66:67]
	v_cvt_pk_bf16_f32 v158, v6, v7
	v_pk_fma_f32 v[2:3], v[2:3], v[70:71], v[4:5] neg_lo:[0,0,1] neg_hi:[0,0,1]
	s_nop 0
	v_cvt_pk_bf16_f32 v154, v2, v3
	v_mul_f32_e32 v2, v0, v104
	v_mul_f32_e32 v3, v2, v230
	v_mul_f32_e32 v2, v0, v107
	v_mul_f32_e32 v5, v2, v100
	v_mov_b32_e32 v100, v231
	v_mul_f32_e32 v4, v5, v68
	v_mul_f32_e32 v8, v3, v68
	v_pk_mul_f32 v[10:11], v[10:11], v[100:101]
	v_mov_b32_e32 v68, v73
	v_pk_mul_f32 v[12:13], v[10:11], v[68:69]
	v_mul_f32_e32 v2, v3, v72
	v_mul_f32_e32 v6, v72, v5
	v_mov_b32_e32 v3, v12
	v_mov_b32_e32 v5, v13
	v_pk_add_f32 v[2:3], v[2:3], v[4:5] neg_lo:[0,1] neg_hi:[0,1]
	v_mov_b32_e32 v72, v69
	v_cvt_pk_bf16_f32 v155, v2, v3
	v_pk_mul_f32 v[2:3], v[72:73], v[10:11]
	s_nop 0
	v_mov_b32_e32 v7, v3
	v_mov_b32_e32 v9, v2
	v_pk_add_f32 v[2:3], v[6:7], v[8:9]
	s_nop 0
	v_cvt_pk_bf16_f32 v159, v2, v3
.LBB0_1244:
	s_or_b64 exec, exec, s[18:19]
	v_mul_hi_i32 v0, v226, s69
	s_load_dwordx2 s[20:21], s[10:11], 0x210
	s_load_dwordx2 s[18:19], s[10:11], 0x1d8
	s_load_dwordx2 s[22:23], s[10:11], 0x200
	v_lshrrev_b32_e32 v2, 31, v0
	v_ashrrev_i32_e32 v0, 2, v0
	v_add_u32_e32 v2, v0, v2
	s_lshl_b32 s24, s2, 8
	v_mul_lo_u32 v0, v2, 24
	s_waitcnt lgkmcnt(0)
	s_add_u32 s20, s20, s24
	v_sub_u32_e32 v0, v226, v0
	v_ashrrev_i32_e32 v3, 31, v2
	v_mov_b32_e32 v4, s26
	s_addc_u32 s21, s21, 0
	v_mad_i64_i32 v[6:7], s[24:25], s18, v4, v[2:3]
	v_cmp_lt_i32_e32 vcc, 15, v0
	v_lshlrev_b32_e32 v4, 3, v0
	s_and_saveexec_b64 s[24:25], vcc
	s_xor_b64 s[24:25], exec, s[24:25]
	v_lshlrev_b64 v[6:7], 7, v[6:7]
	v_lshl_add_u64 v[6:7], s[22:23], 0, v[6:7]
	v_mov_b32_e32 v5, v1
	s_movk_i32 s28, 0xff00
	v_lshl_add_u64 v[6:7], v[4:5], 1, v[6:7]
	s_mov_b32 s29, -1
	v_lshl_add_u64 v[184:185], v[6:7], 0, s[28:29]
	s_or_saveexec_b64 s[24:25], s[24:25]
	v_mov_b64_e32 v[186:187], 0x1000
	s_xor_b64 exec, exec, s[24:25]
	v_lshlrev_b64 v[6:7], 11, v[6:7]
	v_lshl_add_u64 v[6:7], s[20:21], 0, v[6:7]
	v_ashrrev_i32_e32 v5, 31, v4
	v_lshl_add_u64 v[184:185], v[4:5], 1, v[6:7]
	v_mov_b64_e32 v[186:187], 0x10000
	s_or_b64 exec, exec, s[24:25]
	v_add_u32_e32 v3, 0x200, v226
	v_mul_hi_i32 v0, v3, s69
	v_lshrrev_b32_e32 v5, 31, v0
	v_ashrrev_i32_e32 v0, 2, v0
	v_add_u32_e32 v6, v0, v5
	v_mul_lo_u32 v0, v6, 24
	s_mul_hi_i32 s25, s18, s26
	s_mul_i32 s24, s18, s26
	v_sub_u32_e32 v0, v3, v0
	v_ashrrev_i32_e32 v7, 31, v6
	v_lshl_add_u64 v[8:9], s[24:25], 0, v[6:7]
	v_cmp_lt_i32_e32 vcc, 15, v0
	v_lshlrev_b32_e32 v0, 3, v0
	s_and_saveexec_b64 s[26:27], vcc
	s_xor_b64 s[26:27], exec, s[26:27]
	v_lshlrev_b64 v[8:9], 7, v[8:9]
	v_lshl_add_u64 v[8:9], s[22:23], 0, v[8:9]
	s_movk_i32 s28, 0xff00
	v_lshl_add_u64 v[8:9], v[0:1], 1, v[8:9]
	s_mov_b32 s29, -1
	v_lshl_add_u64 v[188:189], v[8:9], 0, s[28:29]
	s_or_saveexec_b64 s[26:27], s[26:27]
	v_mov_b64_e32 v[190:191], 0x1000
	s_xor_b64 exec, exec, s[26:27]
	v_lshlrev_b64 v[8:9], 11, v[8:9]
	v_lshl_add_u64 v[8:9], s[20:21], 0, v[8:9]
	v_ashrrev_i32_e32 v11, 31, v0
	v_mov_b32_e32 v10, v0
	v_lshl_add_u64 v[188:189], v[10:11], 1, v[8:9]
	v_mov_b64_e32 v[190:191], 0x10000
	s_or_b64 exec, exec, s[26:27]
	v_add_u32_e32 v5, 0x400, v226
	v_mul_hi_i32 v7, v5, s69
	v_lshrrev_b32_e32 v8, 31, v7
	v_ashrrev_i32_e32 v7, 2, v7
	v_add_u32_e32 v8, v7, v8
	v_mul_lo_u32 v7, v8, 24
	v_sub_u32_e32 v5, v5, v7
	v_ashrrev_i32_e32 v9, 31, v8
	v_lshl_add_u64 v[12:13], s[24:25], 0, v[8:9]
	v_cmp_lt_i32_e32 vcc, 15, v5
	v_lshlrev_b32_e32 v10, 3, v5
	s_and_saveexec_b64 s[24:25], vcc
	s_xor_b64 s[24:25], exec, s[24:25]
	v_lshlrev_b64 v[12:13], 7, v[12:13]
	v_lshl_add_u64 v[12:13], s[22:23], 0, v[12:13]
	v_mov_b32_e32 v11, v1
	s_movk_i32 s22, 0xff00
	v_lshl_add_u64 v[12:13], v[10:11], 1, v[12:13]
	s_mov_b32 s23, -1
	v_lshl_add_u64 v[192:193], v[12:13], 0, s[22:23]
	s_or_saveexec_b64 s[22:23], s[24:25]
	v_mov_b64_e32 v[194:195], 0x1000
	s_xor_b64 exec, exec, s[22:23]
	v_lshlrev_b64 v[12:13], 11, v[12:13]
	v_lshl_add_u64 v[12:13], s[20:21], 0, v[12:13]
	v_ashrrev_i32_e32 v11, 31, v10
	v_lshl_add_u64 v[192:193], v[10:11], 1, v[12:13]
	v_mov_b64_e32 v[194:195], 0x10000
	s_or_b64 exec, exec, s[22:23]
	v_mad_u64_u32 v[200:201], s[22:23], v8, s90, v[10:11]
	s_load_dwordx2 s[22:23], s[10:11], 0x218
	v_mad_u64_u32 v[196:197], s[20:21], v6, s90, v[0:1]
	v_mad_u64_u32 v[198:199], s[20:21], v2, s90, v[4:5]
	s_lshl_b32 s14, s14, 2
	v_lshlrev_b32_e32 v0, 3, v225
	s_or_b32 s20, s14, 3
	s_ashr_i32 s14, s15, 31
	v_and_b32_e32 v2, 56, v0
	s_lshr_b32 s14, s14, 26
	v_lshlrev_b32_e32 v0, 1, v2
	s_add_i32 s14, s15, s14
	s_lshl_b32 s5, s5, 7
	s_waitcnt lgkmcnt(0)
	v_lshl_add_u64 v[4:5], s[22:23], 0, v[0:1]
	v_ashrrev_i32_e32 v0, 3, v226
	s_movk_i32 s15, 0x44
	v_add_u32_e32 v6, s5, v0
	v_mad_u64_u32 v[204:205], s[22:23], v0, s15, v[2:3]
	v_ashrrev_i32_e32 v0, 3, v3
	v_mad_i64_i32 v[6:7], s[22:23], s18, v6, 0
	v_add_u32_e32 v3, s5, v0
	v_lshl_add_u64 v[202:203], v[6:7], 1, v[4:5]
	v_mad_i64_i32 v[6:7], s[22:23], s18, v3, 0
	v_lshl_add_u64 v[206:207], v[6:7], 1, v[4:5]
	global_load_dwordx4 v[160:163], v[184:185], off
	global_load_dwordx4 v[164:167], v[188:189], off
	global_load_dwordx4 v[168:171], v[192:193], off
	v_readfirstlane_b32 s100, v226
	s_and_b32 s100, s100, 0x1c0
	s_lshl_b32 s100, s100, 2
	s_mov_b32 s22, s100
	s_mov_b32 s23, 0
	v_lshl_add_u64 v[6:7], v[202:203], 0, s[22:23]
	s_xor_b32 s22, s22, 0x800
	global_load_dwordx4 v[172:175], v[6:7], off
	v_lshl_add_u64 v[6:7], v[206:207], 0, s[22:23]
	global_load_dwordx4 v[176:179], v[6:7], off
	s_ashr_i32 s14, s14, 6
	v_mad_u64_u32 v[208:209], s[22:23], v0, s15, v[2:3]
	v_lshlrev_b32_e32 v0, 1, v198
	s_add_i32 s14, s14, -1
	s_barrier
	s_min_i32 s20, s20, s14
	s_add_i32 s20, s20, s19
	s_cmp_lt_i32 s20, 0
	s_waitcnt vmcnt(0)
	ds_write_b128 v0, v[160:163]
	v_lshlrev_b32_e32 v0, 1, v196
	ds_write_b128 v0, v[164:167]
	v_lshlrev_b32_e32 v0, 1, v200
	ds_write_b128 v0, v[168:171]
	v_lshl_add_u32 v0, v204, 1, v220
	ds_write2_b64 v0, v[172:173], v[174:175] offset1:1
	v_lshl_add_u32 v0, v208, 1, v220
	ds_write2_b64 v0, v[176:177], v[178:179] offset1:1
	s_waitcnt lgkmcnt(0)
	s_barrier
	s_cbranch_scc1 .LBB0_1266
	s_lshl_b32 s4, s4, 2
	s_lshl_b32 s3, s3, 2
	s_not_b32 s4, s4
	v_ashrrev_i32_e32 v0, 6, v223
	s_add_i32 s3, s3, s4
	v_add_u32_e32 v191, s19, v0
	v_mul_u32_u24_e32 v0, 0x190, v222
	v_mul_i32_i24_e32 v2, 0xfffffef8, v222
	s_min_i32 s3, s3, s14
	v_mov_b32_e32 v14, v1
	v_mov_b32_e32 v15, v1
	s_movk_i32 s5, 0x190
	v_add3_u32 v197, v0, v2, v224
	s_add_i32 s3, s19, s3
	v_mov_b32_e32 v0, v1
	v_mov_b32_e32 v2, v1
	v_mov_b32_e32 v3, v1
	v_mov_b32_e32 v4, v1
	v_mov_b32_e32 v5, v1
	v_mov_b32_e32 v6, v1
	v_mov_b32_e32 v7, v1
	v_mov_b32_e32 v8, v1
	v_mov_b32_e32 v9, v1
	v_mov_b32_e32 v10, v1
	v_mov_b32_e32 v11, v1
	v_mov_b32_e32 v12, v1
	v_mov_b32_e32 v13, v1
	v_mov_b64_e32 v[46:47], v[14:15]
	v_mov_b64_e32 v[62:63], v[14:15]
	v_mov_b64_e32 v[78:79], v[14:15]
	v_mov_b64_e32 v[30:31], v[14:15]
	v_mad_u32_u24 v195, v222, s5, v102
	s_add_i32 s3, s3, 1
	s_mov_b32 s18, 0
	v_mov_b32_e32 v187, 0
	v_mov_b32_e32 v199, 0xf149f2ca
	s_mov_b32 s82, 64
	v_mov_b64_e32 v[44:45], v[12:13]
	v_mov_b64_e32 v[42:43], v[10:11]
	v_mov_b64_e32 v[40:41], v[8:9]
	v_mov_b64_e32 v[38:39], v[6:7]
	v_mov_b64_e32 v[36:37], v[4:5]
	v_mov_b64_e32 v[34:35], v[2:3]
	v_mov_b64_e32 v[32:33], v[0:1]
	v_mov_b64_e32 v[60:61], v[12:13]
	v_mov_b64_e32 v[58:59], v[10:11]
	v_mov_b64_e32 v[56:57], v[8:9]
	v_mov_b64_e32 v[54:55], v[6:7]
	v_mov_b64_e32 v[52:53], v[4:5]
	v_mov_b64_e32 v[50:51], v[2:3]
	v_mov_b64_e32 v[48:49], v[0:1]
	v_mov_b64_e32 v[76:77], v[12:13]
	v_mov_b64_e32 v[74:75], v[10:11]
	v_mov_b64_e32 v[72:73], v[8:9]
	v_mov_b64_e32 v[70:71], v[6:7]
	v_mov_b64_e32 v[68:69], v[4:5]
	v_mov_b64_e32 v[66:67], v[2:3]
	v_mov_b64_e32 v[64:65], v[0:1]
	v_mov_b64_e32 v[28:29], v[12:13]
	v_mov_b64_e32 v[26:27], v[10:11]
	v_mov_b64_e32 v[24:25], v[8:9]
	v_mov_b64_e32 v[22:23], v[6:7]
	v_mov_b64_e32 v[20:21], v[4:5]
	v_mov_b64_e32 v[18:19], v[2:3]
	v_mov_b64_e32 v[16:17], v[0:1]
.LBB0_1258:
	s_add_i32 s4, s18, 1
	s_cmp_lt_i32 s18, s20
	s_cselect_b64 s[14:15], -1, 0
	s_cmp_ge_i32 s18, s20
	s_cbranch_scc1 .LBB0_1260
	v_mad_u64_u32 v[2:3], s[22:23], v186, s4, 0
	v_lshl_add_u64 v[2:3], v[2:3], 1, v[184:185]
	global_load_dwordx4 v[160:163], v[2:3], off
	v_mad_u64_u32 v[2:3], s[22:23], v190, s4, 0
	v_lshl_add_u64 v[2:3], v[2:3], 1, v[188:189]
	global_load_dwordx4 v[164:167], v[2:3], off
	v_mad_u64_u32 v[2:3], s[22:23], v194, s4, 0
	v_lshl_add_u64 v[2:3], v[2:3], 1, v[192:193]
	s_lshl_b32 s22, s82, 1
	s_xor_b32 s22, s22, s100
	s_mov_b32 s23, 0
	global_load_dwordx4 v[168:171], v[2:3], off
	v_lshl_add_u64 v[2:3], v[202:203], 0, s[22:23]
	s_xor_b32 s22, s22, 0x800
	v_lshl_add_u64 v[4:5], v[206:207], 0, s[22:23]
	global_load_dwordx4 v[172:175], v[2:3], off
	global_load_dwordx4 v[176:179], v[4:5], off
.LBB0_1260:
	v_cmp_le_i32_e32 vcc, s18, v191
	s_and_b32 s5, s18, 1
	s_and_b64 s[22:23], s[16:17], vcc
	s_and_saveexec_b64 s[18:19], s[22:23]
	s_cbranch_execz .LBB0_1262
	s_mul_i32 s21, s5, 0x6400
	v_add_u32_e32 v0, s21, v195
	s_mul_i32 s21, s5, 0x4400
	v_add_u32_e32 v227, s21, v197
	ds_read_b128 v[2:5], v0
	ds_read_b128 v[6:9], v0 offset:12800
	ds_read_b128 v[10:13], v0 offset:32
	ds_read_b128 v[242:245], v0 offset:12832
	ds_read_b128 v[246:249], v0 offset:64
	ds_read_b128 v[250:253], v0 offset:12864
	v_add_u32_e32 v227, 0xc800, v227
	s_waitcnt lgkmcnt(5)
	v_mfma_f32_32x32x16_bf16 v[96:111], v[2:5], v[112:115], 0
	ds_read_b128 v[2:5], v0 offset:96
	s_waitcnt lgkmcnt(5)
	v_mfma_f32_32x32x16_bf16 v[80:95], v[6:9], v[112:115], 0
	ds_read_b128 v[6:9], v0 offset:12896
	s_waitcnt lgkmcnt(5)
	v_mfma_f32_32x32x16_bf16 v[96:111], v[10:13], v[116:119], v[96:111]
	ds_read_b128 v[10:13], v0 offset:128
	s_waitcnt lgkmcnt(5)
	v_mfma_f32_32x32x16_bf16 v[80:95], v[242:245], v[116:119], v[80:95]
	ds_read_b128 v[242:245], v0 offset:12928
	s_waitcnt lgkmcnt(5)
	v_mfma_f32_32x32x16_bf16 v[96:111], v[246:249], v[120:123], v[96:111]
	ds_read_b128 v[246:249], v0 offset:160
	s_waitcnt lgkmcnt(5)
	v_mfma_f32_32x32x16_bf16 v[80:95], v[250:253], v[120:123], v[80:95]
	ds_read_b128 v[250:253], v0 offset:12960
	s_waitcnt lgkmcnt(5)
	v_mfma_f32_32x32x16_bf16 v[96:111], v[2:5], v[124:127], v[96:111]
	ds_read_b128 v[2:5], v0 offset:192
	s_waitcnt lgkmcnt(5)
	v_mfma_f32_32x32x16_bf16 v[80:95], v[6:9], v[124:127], v[80:95]
	ds_read_b128 v[6:9], v0 offset:12992
	s_waitcnt lgkmcnt(5)
	v_mfma_f32_32x32x16_bf16 v[96:111], v[10:13], v[128:131], v[96:111]
	ds_read_b128 v[10:13], v0 offset:224
	s_waitcnt lgkmcnt(5)
	v_mfma_f32_32x32x16_bf16 v[80:95], v[242:245], v[128:131], v[80:95]
	ds_read_b128 v[242:245], v0 offset:13024
	s_waitcnt lgkmcnt(5)
	v_mfma_f32_32x32x16_bf16 v[96:111], v[246:249], v[132:135], v[96:111]
	ds_read_b128 v[246:249], v0 offset:256
	s_waitcnt lgkmcnt(5)
	v_mfma_f32_32x32x16_bf16 v[80:95], v[250:253], v[132:135], v[80:95]
	ds_read_b128 v[250:253], v0 offset:13056
	s_waitcnt lgkmcnt(5)
	v_mfma_f32_32x32x16_bf16 v[96:111], v[2:5], v[136:139], v[96:111]
	ds_read_b128 v[2:5], v0 offset:288
	s_waitcnt lgkmcnt(5)
	v_mfma_f32_32x32x16_bf16 v[80:95], v[6:9], v[136:139], v[80:95]
	ds_read_b128 v[6:9], v0 offset:13088
	s_waitcnt lgkmcnt(5)
	v_mfma_f32_32x32x16_bf16 v[96:111], v[10:13], v[140:143], v[96:111]
	ds_read_b128 v[10:13], v0 offset:320
	s_waitcnt lgkmcnt(5)
	v_mfma_f32_32x32x16_bf16 v[80:95], v[242:245], v[140:143], v[80:95]
	ds_read_b128 v[242:245], v0 offset:13120
	s_waitcnt lgkmcnt(5)
	v_mfma_f32_32x32x16_bf16 v[96:111], v[246:249], v[144:147], v[96:111]
	ds_read_b128 v[246:249], v0 offset:352
	s_waitcnt lgkmcnt(5)
	v_mfma_f32_32x32x16_bf16 v[80:95], v[250:253], v[144:147], v[80:95]
	ds_read_b128 v[250:253], v0 offset:13152
	s_waitcnt lgkmcnt(5)
	v_mfma_f32_32x32x16_bf16 v[96:111], v[2:5], v[152:155], v[96:111]
	s_waitcnt lgkmcnt(4)
	v_mfma_f32_32x32x16_bf16 v[80:95], v[6:9], v[152:155], v[80:95]
	s_waitcnt lgkmcnt(3)
	v_mfma_f32_32x32x16_bf16 v[96:111], v[10:13], v[148:151], v[96:111]
	s_waitcnt lgkmcnt(2)
	v_mfma_f32_32x32x16_bf16 v[80:95], v[242:245], v[148:151], v[80:95]
	ds_read_b64 v[242:243], v227
	ds_read_b64 v[244:245], v227 offset:16
	s_waitcnt lgkmcnt(3)
	v_mfma_f32_32x32x16_bf16 v[96:111], v[246:249], v[156:159], v[96:111]
	ds_read_b64 v[246:247], v227 offset:4352
	ds_read_b64 v[248:249], v227 offset:4368
	s_waitcnt lgkmcnt(4)
	v_mfma_f32_32x32x16_bf16 v[80:95], v[250:253], v[156:159], v[80:95]
	ds_read_b64 v[250:251], v227 offset:8704
	ds_read_b64 v[252:253], v227 offset:8720
	v_and_b32_e32 v3, 64, v218
	v_xor_b32_e32 v2, 32, v218
	v_add_u32_e32 v3, 64, v3
	v_cmp_lt_i32_e32 vcc, v2, v3
	s_nop 1
	v_cndmask_b32_e32 v2, v218, v2, vcc
	v_lshlrev_b32_e32 v13, 2, v2
	s_nop 1
	v_max3_f32 v0, v96, v97, v98
	v_max3_f32 v2, v80, v81, v82
	v_max3_f32 v0, v0, v99, v100
	v_max3_f32 v2, v2, v83, v84
	v_max3_f32 v0, v0, v101, v102
	v_max3_f32 v2, v2, v85, v86
	v_max3_f32 v0, v0, v103, v104
	v_max3_f32 v2, v2, v87, v88
	v_max3_f32 v0, v0, v105, v106
	v_max3_f32 v2, v2, v89, v90
	v_max3_f32 v0, v0, v107, v108
	v_max3_f32 v2, v2, v91, v92
	v_max3_f32 v0, v0, v109, v110
	v_max3_f32 v2, v2, v93, v94
	v_max3_f32 v0, v0, v111, v95
	v_max_f32_e32 v0, v0, v2
	ds_bpermute_b32 v2, v13, v0
	s_waitcnt lgkmcnt(0)
	v_max_f32_e32 v0, v0, v2
	v_sub_f32_e32 v2, v0, v199
	v_mov_b32_e32 v12, v199
	v_cmp_lt_f32_e32 vcc, 0x41000000, v2
	s_cbranch_vccz .Lattn_nr_s0
	v_max_f32_e32 v12, v199, v0
	v_sub_f32_e32 v2, v199, v12
	v_exp_f32_e32 v2, v2
	v_mov_b32_e32 v199, v12
	v_mul_f32_e32 v187, v187, v2
	v_mul_f32_e32 v16, v2, v16
	v_mul_f32_e32 v17, v2, v17
	v_mul_f32_e32 v18, v2, v18
	v_mul_f32_e32 v19, v2, v19
	v_mul_f32_e32 v20, v2, v20
	v_mul_f32_e32 v21, v2, v21
	v_mul_f32_e32 v22, v2, v22
	v_mul_f32_e32 v23, v2, v23
	v_mul_f32_e32 v24, v2, v24
	v_mul_f32_e32 v25, v2, v25
	v_mul_f32_e32 v26, v2, v26
	v_mul_f32_e32 v27, v2, v27
	v_mul_f32_e32 v28, v2, v28
	v_mul_f32_e32 v29, v2, v29
	v_mul_f32_e32 v30, v2, v30
	v_mul_f32_e32 v31, v2, v31
	v_mul_f32_e32 v32, v2, v32
	v_mul_f32_e32 v33, v2, v33
	v_mul_f32_e32 v34, v2, v34
	v_mul_f32_e32 v35, v2, v35
	v_mul_f32_e32 v36, v2, v36
	v_mul_f32_e32 v37, v2, v37
	v_mul_f32_e32 v38, v2, v38
	v_mul_f32_e32 v39, v2, v39
	v_mul_f32_e32 v40, v2, v40
	v_mul_f32_e32 v41, v2, v41
	v_mul_f32_e32 v42, v2, v42
	v_mul_f32_e32 v43, v2, v43
	v_mul_f32_e32 v44, v2, v44
	v_mul_f32_e32 v45, v2, v45
	v_mul_f32_e32 v46, v2, v46
	v_mul_f32_e32 v47, v2, v47
	v_mul_f32_e32 v48, v2, v48
	v_mul_f32_e32 v49, v2, v49
	v_mul_f32_e32 v50, v2, v50
	v_mul_f32_e32 v51, v2, v51
	v_mul_f32_e32 v52, v2, v52
	v_mul_f32_e32 v53, v2, v53
	v_mul_f32_e32 v54, v2, v54
	v_mul_f32_e32 v55, v2, v55
	v_mul_f32_e32 v56, v2, v56
	v_mul_f32_e32 v57, v2, v57
	v_mul_f32_e32 v58, v2, v58
	v_mul_f32_e32 v59, v2, v59
	v_mul_f32_e32 v60, v2, v60
	v_mul_f32_e32 v61, v2, v61
	v_mul_f32_e32 v62, v2, v62
	v_mul_f32_e32 v63, v2, v63
	v_mul_f32_e32 v64, v2, v64
	v_mul_f32_e32 v65, v2, v65
	v_mul_f32_e32 v66, v2, v66
	v_mul_f32_e32 v67, v2, v67
	v_mul_f32_e32 v68, v2, v68
	v_mul_f32_e32 v69, v2, v69
	v_mul_f32_e32 v70, v2, v70
	v_mul_f32_e32 v71, v2, v71
	v_mul_f32_e32 v72, v2, v72
	v_mul_f32_e32 v73, v2, v73
	v_mul_f32_e32 v74, v2, v74
	v_mul_f32_e32 v75, v2, v75
	v_mul_f32_e32 v76, v2, v76
	v_mul_f32_e32 v77, v2, v77
	v_mul_f32_e32 v78, v2, v78
	v_mul_f32_e32 v79, v2, v79
.Lattn_nr_s0:
	v_sub_f32_e32 v0, v96, v12
	v_sub_f32_e32 v3, v97, v12
	v_exp_f32_e32 v2, v0
	v_sub_f32_e32 v0, v80, v12
	v_exp_f32_e32 v15, v3
	v_sub_f32_e32 v3, v81, v12
	v_exp_f32_e32 v201, v0
	v_exp_f32_e32 v199, v3
	v_sub_f32_e32 v3, v98, v12
	v_exp_f32_e32 v80, v3
	v_sub_f32_e32 v3, v82, v12
	v_exp_f32_e32 v205, v3
	v_sub_f32_e32 v3, v99, v12
	v_sub_f32_e32 v6, v108, v12
	v_exp_f32_e32 v209, v3
	v_sub_f32_e32 v3, v100, v12
	v_exp_f32_e32 v210, v3
	v_sub_f32_e32 v3, v101, v12
	v_exp_f32_e32 v211, v3
	v_sub_f32_e32 v3, v102, v12
	v_exp_f32_e32 v11, v3
	v_sub_f32_e32 v3, v103, v12
	v_exp_f32_e32 v10, v3
	v_sub_f32_e32 v4, v106, v12
	v_exp_f32_e32 v7, v6
	v_sub_f32_e32 v6, v109, v12
	v_sub_f32_e32 v3, v104, v12
	v_sub_f32_e32 v81, v105, v12
	v_exp_f32_e32 v5, v4
	v_sub_f32_e32 v4, v107, v12
	v_sub_f32_e32 v8, v110, v12
	v_cvt_pk_bf16_f32 v103, v11, v10
	v_cvt_pk_bf16_f32 v102, v210, v211
	v_cvt_pk_bf16_f32 v101, v80, v209
	v_cvt_pk_bf16_f32 v100, v2, v15
	v_exp_f32_e32 v9, v8
	s_nop 0
	v_mfma_f32_32x32x16_bf16 v[64:79], v[242:245], v[100:103], v[64:79]
	ds_read_b64 v[242:243], v227 offset:13056
	ds_read_b64 v[244:245], v227 offset:13072
	v_sub_f32_e32 v8, v111, v12
	v_mfma_f32_32x32x16_bf16 v[48:63], v[246:249], v[100:103], v[48:63]
	ds_read_b64 v[246:247], v227 offset:32
	ds_read_b64 v[248:249], v227 offset:48
	v_add_f32_e32 v14, v2, v201
	v_exp_f32_e32 v3, v3
	v_mfma_f32_32x32x16_bf16 v[32:47], v[250:253], v[100:103], v[32:47]
	ds_read_b64 v[250:251], v227 offset:8736
	ds_read_b64 v[252:253], v227 offset:8752
	v_exp_f32_e32 v6, v6
	v_exp_f32_e32 v8, v8
	v_exp_f32_e32 v4, v4
	v_exp_f32_e32 v2, v81
	v_add_f32_e32 v14, 0, v14
	v_add_f32_e32 v15, v15, v199
	v_add_f32_e32 v14, v15, v14
	v_add_f32_e32 v15, v80, v205
	v_sub_f32_e32 v80, v83, v12
	v_exp_f32_e32 v212, v80
	s_waitcnt lgkmcnt(4)
	v_mfma_f32_32x32x16_bf16 v[16:31], v[242:245], v[100:103], v[16:31]
	ds_read_b64 v[242:243], v227 offset:4384
	ds_read_b64 v[244:245], v227 offset:4400
	v_cvt_pk_bf16_f32 v103, v9, v8
	v_cvt_pk_bf16_f32 v102, v7, v6
	v_cvt_pk_bf16_f32 v101, v5, v4
	v_cvt_pk_bf16_f32 v100, v3, v2
	v_add_f32_e32 v14, v15, v14
	v_add_f32_e32 v15, v209, v212
	s_waitcnt lgkmcnt(4)
	v_mfma_f32_32x32x16_bf16 v[64:79], v[246:249], v[100:103], v[64:79]
	ds_read_b64 v[246:247], v227 offset:13088
	ds_read_b64 v[248:249], v227 offset:13104
	v_sub_f32_e32 v84, v84, v12
	v_exp_f32_e32 v84, v84
	s_waitcnt lgkmcnt(4)
	v_mfma_f32_32x32x16_bf16 v[32:47], v[250:253], v[100:103], v[32:47]
	ds_read_b64 v[250:251], v227 offset:64
	ds_read_b64 v[252:253], v227 offset:80
	s_waitcnt lgkmcnt(4)
	v_mfma_f32_32x32x16_bf16 v[48:63], v[242:245], v[100:103], v[48:63]
	ds_read_b64 v[242:243], v227 offset:4416
	ds_read_b64 v[244:245], v227 offset:4432
	v_add_f32_e32 v104, v15, v14
	v_sub_f32_e32 v14, v85, v12
	v_exp_f32_e32 v85, v14
	v_sub_f32_e32 v14, v86, v12
	v_exp_f32_e32 v15, v14
	v_sub_f32_e32 v14, v87, v12
	v_exp_f32_e32 v14, v14
	s_waitcnt lgkmcnt(4)
	v_mfma_f32_32x32x16_bf16 v[16:31], v[246:249], v[100:103], v[16:31]
	ds_read_b64 v[246:247], v227 offset:8768
	ds_read_b64 v[248:249], v227 offset:8784
	v_add_f32_e32 v105, v210, v84
	v_add_f32_e32 v100, v105, v104
	v_add_f32_e32 v101, v211, v85
	v_cvt_pk_bf16_f32 v87, v15, v14
	v_cvt_pk_bf16_f32 v86, v84, v85
	v_cvt_pk_bf16_f32 v85, v205, v212
	v_cvt_pk_bf16_f32 v84, v201, v199
	v_pk_add_f32 v[10:11], v[10:11], v[14:15]
	v_sub_f32_e32 v14, v90, v12
	s_waitcnt lgkmcnt(4)
	v_mfma_f32_32x32x16_bf16 v[64:79], v[250:253], v[84:87], v[64:79]
	ds_read_b64 v[250:251], v227 offset:13120
	ds_read_b64 v[252:253], v227 offset:13136
	v_add_f32_e32 v80, v101, v100
	v_add_f32_e32 v11, v11, v80
	v_add_f32_e32 v100, v10, v11
	v_sub_f32_e32 v10, v88, v12
	v_sub_f32_e32 v88, v92, v12
	v_exp_f32_e32 v11, v10
	s_waitcnt lgkmcnt(4)
	v_mfma_f32_32x32x16_bf16 v[48:63], v[242:245], v[84:87], v[48:63]
	ds_read_b64 v[242:243], v227 offset:8800
	ds_read_b64 v[244:245], v227 offset:8816
	v_sub_f32_e32 v10, v89, v12
	v_exp_f32_e32 v15, v14
	v_sub_f32_e32 v14, v91, v12
	v_exp_f32_e32 v97, v88
	v_exp_f32_e32 v10, v10
	v_exp_f32_e32 v14, v14
	s_waitcnt lgkmcnt(4)
	v_mfma_f32_32x32x16_bf16 v[32:47], v[246:249], v[84:87], v[32:47]
	ds_read_b64 v[246:247], v227 offset:96
	ds_read_b64 v[248:249], v227 offset:112
	v_sub_f32_e32 v80, v93, v12
	v_add_f32_e64 v2, v2, v10
	v_add_f32_e64 v3, v3, v11
	v_exp_f32_e32 v96, v80
	v_add_f32_e32 v3, v3, v100
	v_sub_f32_e32 v80, v94, v12
	v_exp_f32_e32 v93, v80
	v_sub_f32_e32 v80, v95, v12
	s_waitcnt lgkmcnt(4)
	v_mfma_f32_32x32x16_bf16 v[16:31], v[250:253], v[84:87], v[16:31]
	ds_read_b64 v[250:251], v227 offset:4448
	ds_read_b64 v[252:253], v227 offset:4464
	v_cvt_pk_bf16_f32 v84, v11, v10
	v_add_f32_e32 v10, v2, v3
	v_add_f32_e64 v2, v4, v14
	v_add_f32_e64 v3, v5, v15
	v_exp_f32_e32 v92, v80
	v_add_f32_e32 v3, v3, v10
	v_add_f32_e32 v10, v2, v3
	v_cvt_pk_bf16_f32 v87, v93, v92
	v_cvt_pk_bf16_f32 v86, v97, v96
	v_cvt_pk_bf16_f32 v85, v15, v14
	s_waitcnt lgkmcnt(4)
	s_nop 0
	v_mfma_f32_32x32x16_bf16 v[32:47], v[242:245], v[84:87], v[32:47]
	ds_read_b64 v[242:243], v227 offset:13152
	ds_read_b64 v[244:245], v227 offset:13168
	v_add_f32_e64 v6, v6, v96
	v_add_f32_e64 v7, v7, v97
	v_mov_b32_e32 v199, v12
	v_add_f32_e32 v7, v7, v10
	v_add_f32_e32 v10, v6, v7
	v_pk_add_f32 v[6:7], v[8:9], v[92:93]
	s_nop 0
	v_add_f32_e32 v7, v7, v10
	v_add_f32_e32 v6, v6, v7
	s_waitcnt lgkmcnt(4)
	v_mfma_f32_32x32x16_bf16 v[64:79], v[246:249], v[84:87], v[64:79]
	ds_bpermute_b32 v7, v13, v6
	s_waitcnt lgkmcnt(0)
	v_add_f32_e32 v6, v6, v7
	v_add_f32_e32 v6, v6, v187
	v_mfma_f32_32x32x16_bf16 v[48:63], v[250:253], v[84:87], v[48:63]
	v_mov_b32_e32 v187, v6
	v_mfma_f32_32x32x16_bf16 v[16:31], v[242:245], v[84:87], v[16:31]

	.amdhsa_kernel _Z14fwd_megakernel6Params
		.amdhsa_group_segment_fixed_size 163604
		.amdhsa_private_segment_fixed_size 0
		.amdhsa_kernarg_size 1072
		.amdhsa_user_sgpr_count 2
		.amdhsa_user_sgpr_dispatch_ptr 0
		.amdhsa_user_sgpr_queue_ptr 0
		.amdhsa_user_sgpr_kernarg_segment_ptr 1
		.amdhsa_user_sgpr_dispatch_id 0
		.amdhsa_user_sgpr_kernarg_preload_length 0
		.amdhsa_user_sgpr_kernarg_preload_offset 0
		.amdhsa_user_sgpr_private_segment_size 0
		.amdhsa_uses_dynamic_stack 0
		.amdhsa_enable_private_segment 0
		.amdhsa_system_sgpr_workgroup_id_x 1
		.amdhsa_system_sgpr_workgroup_id_y 0
		.amdhsa_system_sgpr_workgroup_id_z 0
		.amdhsa_system_sgpr_workgroup_info 0
		.amdhsa_system_vgpr_workitem_id 2
		.amdhsa_next_free_vgpr 256
		.amdhsa_next_free_sgpr 102
		.amdhsa_accum_offset 256
		.amdhsa_reserve_vcc 1
		.amdhsa_float_round_mode_32 0
		.amdhsa_float_round_mode_16_64 0
		.amdhsa_float_denorm_mode_32 3
		.amdhsa_float_denorm_mode_16_64 3
		.amdhsa_dx10_clamp 1
		.amdhsa_ieee_mode 1
		.amdhsa_fp16_overflow 0
		.amdhsa_tg_split 0
		.amdhsa_exception_fp_ieee_invalid_op 0
		.amdhsa_exception_fp_denorm_src 0
		.amdhsa_exception_fp_ieee_div_zero 0
		.amdhsa_exception_fp_ieee_overflow 0
		.amdhsa_exception_fp_ieee_underflow 0
		.amdhsa_exception_fp_ieee_inexact 0
		.amdhsa_exception_int_div_zero 0
	.end_amdhsa_kernel

amdhsa.kernels:
  - .agpr_count:     0
    .args:
      - .offset:         0
        .size:           816
        .value_kind:     by_value
      - .offset:         816
        .size:           4
        .value_kind:     hidden_block_count_x
      - .offset:         820
        .size:           4
        .value_kind:     hidden_block_count_y
      - .offset:         824
        .size:           4
        .value_kind:     hidden_block_count_z
      - .offset:         828
        .size:           2
        .value_kind:     hidden_group_size_x
      - .offset:         830
        .size:           2
        .value_kind:     hidden_group_size_y
      - .offset:         832
        .size:           2
        .value_kind:     hidden_group_size_z
      - .offset:         834
        .size:           2
        .value_kind:     hidden_remainder_x
      - .offset:         836
        .size:           2
        .value_kind:     hidden_remainder_y
      - .offset:         838
        .size:           2
        .value_kind:     hidden_remainder_z
      - .offset:         856
        .size:           8
        .value_kind:     hidden_global_offset_x
      - .offset:         864
        .size:           8
        .value_kind:     hidden_global_offset_y
      - .offset:         872
        .size:           8
        .value_kind:     hidden_global_offset_z
      - .offset:         880
        .size:           2
        .value_kind:     hidden_grid_dims
      - .offset:         904
        .size:           8
        .value_kind:     hidden_multigrid_sync_arg
    .group_segment_fixed_size: 163604
    .kernarg_segment_align: 8
    .kernarg_segment_size: 1072
    .language:       OpenCL C
    .language_version:
      - 2
      - 0
    .max_flat_workgroup_size: 512
    .name:           _Z14fwd_megakernel6Params
    .private_segment_fixed_size: 0
    .sgpr_count:     108
    .sgpr_spill_count: 17
    .symbol:         _Z14fwd_megakernel6Params.kd
    .uniform_work_group_size: 1
    .uses_dynamic_stack: false
    .vgpr_count:     256
    .vgpr_spill_count: 0
    .wavefront_size: 64
